# X22: X13 + GEMM MMA blocks reordered so each accumulator's two k-step MFMAs issue back to back (accumulate chain forwarding)
# speedup vs baseline: 1.0140x; 1.0110x over previous
; #define PG8_STAGE(bufoff, gbase, voff) do { _Pragma("unroll") for (int _i = 0; _i < 2; ++_i) \
;         __builtin_amdgcn_global_load_lds((const unsigned*)((const char*)(gbase) + (voff)[_i]), (PG8_LAS unsigned*)(lds + (bufoff) + ldsw + _i * 8192), 16, 0, 0); } while (0)
; #define PG8_LDA(dst, b, h) do { _Pragma("unroll") for (int m = 0; m < 4; ++m) _Pragma("unroll") for (int k = 0; k < 2; ++k) dst[m][k] = *(const PG8_LAS bf16x8*)(lds + PG8_SA(b, h) + aoff + m * 2048 + k * 1024); } while (0)
; #define PG8_LDB(dst, b, h) do { _Pragma("unroll") for (int n = 0; n < 2; ++n) _Pragma("unroll") for (int k = 0; k < 2; ++k) dst[n][k] = *(const PG8_LAS bf16x8*)(lds + PG8_SB(b, h) + boff + n * 2048 + k * 1024); } while (0)
; #define PG8_MMA(ai, bj, At, Bt) do { __builtin_amdgcn_s_setprio(1); _Pragma("unroll") for (int m = 0; m < 4; ++m) _Pragma("unroll") for (int n = 0; n < 2; ++n) _Pragma("unroll") for (int k = 0; k < 2; ++k) \
;         acc[ai][bj][m][n] = __builtin_amdgcn_mfma_f32_16x16x32_bf16(Bt[n][k], At[m][k], acc[ai][bj][m][n], 0, 0, 0); __builtin_amdgcn_s_setprio(0); } while (0)
; #define PG8_WAIT_V(n) asm volatile("s_waitcnt vmcnt(" #n ")" ::: "memory")
; #define PG8_WAIT_L(n) asm volatile("s_waitcnt lgkmcnt(" #n ")" ::: "memory")
; #define PG8_BAR __builtin_amdgcn_s_barrier()
; #define PG8_SCHED __builtin_amdgcn_sched_barrier(0)
; template <class Epi, class Sched, bool ALIGN_EPI = false, bool SP2 = false>
; __device__ __forceinline__ void gemm_phase(PG8_LAS unsigned char* lds, const Gemm g, const Sched& S, const Epi& E) {
;     ...
;             PG8_LDB(B0, 0, 0); PG8_LDB(B1, 0, 1); PG8_SCHED; PG8_LDA(At, 0, 0); PG8_STAGE(PG8_SA(1, 1), a1 + hstep, voffA);
;             PG8_WAIT_V(8); PG8_WAIT_L(0); PG8_BAR; PG8_MMA(0, 0, At, B0); PG8_MMA(0, 1, At, B1); PG8_BAR; PG8_SCHED;
.LBB0_216:
	s_add_u32 s22, s54, 0xfff80080
	s_addc_u32 s23, s55, -1
	s_add_i32 s34, 0, 0x10000
	s_cmp_eq_u32 s20, 28
	s_cselect_b32 s57, s47, s23
	s_cselect_b32 s56, vcc_lo, s22
	v_add_u32_e32 v152, s34, v155
	s_cselect_b32 s23, s49, s77
	s_cselect_b32 s22, vcc_hi, s71
	s_add_i32 s4, 0, 0x14000
	ds_read_b128 v[144:147], v152
	ds_read_b128 v[148:151], v152 offset:1024
	ds_read_b128 v[168:171], v152 offset:2048
	ds_read_b128 v[172:175], v152 offset:3072
	v_add_u32_e32 v152, s4, v155
	ds_read_b128 v[176:179], v152
	ds_read_b128 v[180:183], v152 offset:1024
	ds_read_b128 v[184:187], v152 offset:2048
	ds_read_b128 v[188:191], v152 offset:3072
	v_lshl_add_u64 v[152:153], s[54:55], 0, v[140:141]
	s_add_i32 m0, s66, 0xc000
	ds_read_b128 v[212:215], v157
	ds_read_b128 v[216:219], v157 offset:1024
	ds_read_b128 v[220:223], v157 offset:2048
	ds_read_b128 v[224:227], v157 offset:3072
	ds_read_b128 v[228:231], v157 offset:4096
	ds_read_b128 v[232:235], v157 offset:5120
	ds_read_b128 v[236:239], v157 offset:6144
	ds_read_b128 v[240:243], v157 offset:7168
	global_load_lds_dwordx4 v[152:153], off
	v_lshl_add_u64 v[152:153], s[54:55], 0, v[142:143]
	s_add_i32 m0, s66, 0xe000
	s_nop 0
	global_load_lds_dwordx4 v[152:153], off
	s_waitcnt vmcnt(8)
	s_waitcnt lgkmcnt(0)
	s_barrier
	v_mfma_f32_16x16x32_bf16 v[126:129], v[144:147], v[212:215], v[126:129]
	v_mfma_f32_16x16x32_bf16 v[126:129], v[148:151], v[216:219], v[126:129]
	v_mfma_f32_16x16x32_bf16 v[118:121], v[168:171], v[212:215], v[118:121]
	v_mfma_f32_16x16x32_bf16 v[118:121], v[172:175], v[216:219], v[118:121]
	v_mfma_f32_16x16x32_bf16 v[110:113], v[144:147], v[220:223], v[110:113]
	v_mfma_f32_16x16x32_bf16 v[110:113], v[148:151], v[224:227], v[110:113]
	v_mfma_f32_16x16x32_bf16 v[102:105], v[168:171], v[220:223], v[102:105]
	v_mfma_f32_16x16x32_bf16 v[102:105], v[172:175], v[224:227], v[102:105]
	v_mfma_f32_16x16x32_bf16 v[94:97], v[144:147], v[228:231], v[94:97]
	v_mfma_f32_16x16x32_bf16 v[94:97], v[148:151], v[232:235], v[94:97]
	v_mfma_f32_16x16x32_bf16 v[86:89], v[168:171], v[228:231], v[86:89]
	v_mfma_f32_16x16x32_bf16 v[86:89], v[172:175], v[232:235], v[86:89]
	v_mfma_f32_16x16x32_bf16 v[78:81], v[144:147], v[236:239], v[78:81]
	v_mfma_f32_16x16x32_bf16 v[78:81], v[148:151], v[240:243], v[78:81]
	v_mfma_f32_16x16x32_bf16 v[70:73], v[168:171], v[236:239], v[70:73]
	v_mfma_f32_16x16x32_bf16 v[70:73], v[172:175], v[240:243], v[70:73]
	v_mfma_f32_16x16x32_bf16 v[130:133], v[176:179], v[212:215], v[130:133]
	v_mfma_f32_16x16x32_bf16 v[130:133], v[180:183], v[216:219], v[130:133]
	v_mfma_f32_16x16x32_bf16 v[122:125], v[184:187], v[212:215], v[122:125]
	v_mfma_f32_16x16x32_bf16 v[122:125], v[188:191], v[216:219], v[122:125]
	v_mfma_f32_16x16x32_bf16 v[114:117], v[176:179], v[220:223], v[114:117]
	v_mfma_f32_16x16x32_bf16 v[114:117], v[180:183], v[224:227], v[114:117]
	v_mfma_f32_16x16x32_bf16 v[106:109], v[184:187], v[220:223], v[106:109]
	v_mfma_f32_16x16x32_bf16 v[106:109], v[188:191], v[224:227], v[106:109]
	v_mfma_f32_16x16x32_bf16 v[98:101], v[176:179], v[228:231], v[98:101]
	v_mfma_f32_16x16x32_bf16 v[98:101], v[180:183], v[232:235], v[98:101]
	v_mfma_f32_16x16x32_bf16 v[90:93], v[184:187], v[228:231], v[90:93]
	v_mfma_f32_16x16x32_bf16 v[90:93], v[188:191], v[232:235], v[90:93]
	v_mfma_f32_16x16x32_bf16 v[82:85], v[176:179], v[236:239], v[82:85]
	v_mfma_f32_16x16x32_bf16 v[82:85], v[180:183], v[240:243], v[82:85]
	v_mfma_f32_16x16x32_bf16 v[74:77], v[184:187], v[236:239], v[74:77]
	v_mfma_f32_16x16x32_bf16 v[74:77], v[188:191], v[240:243], v[74:77]
	s_barrier
	s_add_i32 s5, s34, s65
	v_lshl_add_u64 v[152:153], s[22:23], 0, v[4:5]
	s_mov_b32 m0, s5
	ds_read_b128 v[212:215], v157 offset:16384
	ds_read_b128 v[216:219], v157 offset:17408
	ds_read_b128 v[220:223], v157 offset:18432
	ds_read_b128 v[224:227], v157 offset:19456
	ds_read_b128 v[228:231], v157 offset:20480
	ds_read_b128 v[232:235], v157 offset:21504
	ds_read_b128 v[236:239], v157 offset:22528
	ds_read_b128 v[240:243], v157 offset:23552
	global_load_lds_dwordx4 v[152:153], off
	s_add_i32 m0, s5, 0x2000
	s_add_u32 s34, s22, 0x80000
	v_lshl_add_u64 v[192:193], s[22:23], 0, v[2:3]
	s_addc_u32 s35, s23, 0
	s_add_i32 s4, s4, s65
	global_load_lds_dwordx4 v[192:193], off
	v_lshl_add_u64 v[244:245], s[34:35], 0, v[4:5]
	s_mov_b32 m0, s4
	v_lshl_add_u64 v[246:247], s[56:57], 0, v[134:135]
	global_load_lds_dwordx4 v[244:245], off
	v_lshl_add_u64 v[244:245], s[34:35], 0, v[2:3]
	s_add_i32 m0, s4, 0x2000
	s_nop 0
	global_load_lds_dwordx4 v[244:245], off
	v_lshl_add_u64 v[244:245], s[56:57], 0, v[136:137]
	s_mov_b32 m0, s66
	s_nop 0
	global_load_lds_dwordx4 v[244:245], off
	s_mov_b32 m0, s67
	s_nop 0
	global_load_lds_dwordx4 v[246:247], off
	s_waitcnt vmcnt(8)
	s_waitcnt lgkmcnt(0)
	s_barrier
; #define PG8_STAGE(bufoff, gbase, voff) do { _Pragma("unroll") for (int _i = 0; _i < 2; ++_i) \
;         __builtin_amdgcn_global_load_lds((const unsigned*)((const char*)(gbase) + (voff)[_i]), (PG8_LAS unsigned*)(lds + (bufoff) + ldsw + _i * 8192), 16, 0, 0); } while (0)
; #define PG8_LDA(dst, b, h) do { _Pragma("unroll") for (int m = 0; m < 4; ++m) _Pragma("unroll") for (int k = 0; k < 2; ++k) dst[m][k] = *(const PG8_LAS bf16x8*)(lds + PG8_SA(b, h) + aoff + m * 2048 + k * 1024); } while (0)
; #define PG8_LDB(dst, b, h) do { _Pragma("unroll") for (int n = 0; n < 2; ++n) _Pragma("unroll") for (int k = 0; k < 2; ++k) dst[n][k] = *(const PG8_LAS bf16x8*)(lds + PG8_SB(b, h) + boff + n * 2048 + k * 1024); } while (0)
; #define PG8_MMA(ai, bj, At, Bt) do { __builtin_amdgcn_s_setprio(1); _Pragma("unroll") for (int m = 0; m < 4; ++m) _Pragma("unroll") for (int n = 0; n < 2; ++n) _Pragma("unroll") for (int k = 0; k < 2; ++k) \
;         acc[ai][bj][m][n] = __builtin_amdgcn_mfma_f32_16x16x32_bf16(Bt[n][k], At[m][k], acc[ai][bj][m][n], 0, 0, 0); __builtin_amdgcn_s_setprio(0); } while (0)
; #define PG8_WAIT_V(n) asm volatile("s_waitcnt vmcnt(" #n ")" ::: "memory")
; #define PG8_WAIT_L(n) asm volatile("s_waitcnt lgkmcnt(" #n ")" ::: "memory")
; #define PG8_BAR __builtin_amdgcn_s_barrier()
; #define PG8_SCHED __builtin_amdgcn_sched_barrier(0)
; template <class Epi, class Sched, bool ALIGN_EPI = false, bool SP2 = false>
; __device__ __forceinline__ void gemm_phase(PG8_LAS unsigned char* lds, const Gemm g, const Sched& S, const Epi& E) {
;     ...
;             PG8_WAIT_V(8); PG8_WAIT_L(0); PG8_BAR; PG8_MMA(1, 0, At, B0); PG8_MMA(1, 1, At, B1); PG8_BAR; PG8_SCHED;
;             PG8_LDB(B0, 1, 0); PG8_LDB(B1, 1, 1); PG8_SCHED; PG8_LDA(At, 1, 0); PG8_STAGE(PG8_SA(0, 1), a2 + hstep, voffA);
;             PG8_WAIT_V(8); PG8_WAIT_L(0); PG8_BAR; PG8_MMA(0, 0, At, B0); PG8_MMA(0, 1, At, B1); PG8_BAR; PG8_SCHED;
	v_mfma_f32_16x16x32_bf16 v[62:65], v[144:147], v[212:215], v[62:65]
	v_mfma_f32_16x16x32_bf16 v[62:65], v[148:151], v[216:219], v[62:65]
	v_mfma_f32_16x16x32_bf16 v[54:57], v[168:171], v[212:215], v[54:57]
	v_mfma_f32_16x16x32_bf16 v[54:57], v[172:175], v[216:219], v[54:57]
	v_mfma_f32_16x16x32_bf16 v[46:49], v[144:147], v[220:223], v[46:49]
	v_mfma_f32_16x16x32_bf16 v[46:49], v[148:151], v[224:227], v[46:49]
	v_mfma_f32_16x16x32_bf16 v[38:41], v[168:171], v[220:223], v[38:41]
	v_mfma_f32_16x16x32_bf16 v[38:41], v[172:175], v[224:227], v[38:41]
	v_mfma_f32_16x16x32_bf16 v[30:33], v[144:147], v[228:231], v[30:33]
	v_mfma_f32_16x16x32_bf16 v[30:33], v[148:151], v[232:235], v[30:33]
	v_mfma_f32_16x16x32_bf16 v[22:25], v[168:171], v[228:231], v[22:25]
	v_mfma_f32_16x16x32_bf16 v[22:25], v[172:175], v[232:235], v[22:25]
	v_mfma_f32_16x16x32_bf16 v[14:17], v[144:147], v[236:239], v[14:17]
	v_mfma_f32_16x16x32_bf16 v[14:17], v[148:151], v[240:243], v[14:17]
	v_mfma_f32_16x16x32_bf16 v[6:9], v[168:171], v[236:239], v[6:9]
	v_mfma_f32_16x16x32_bf16 v[6:9], v[172:175], v[240:243], v[6:9]
	v_mfma_f32_16x16x32_bf16 v[66:69], v[176:179], v[212:215], v[66:69]
	v_mfma_f32_16x16x32_bf16 v[66:69], v[180:183], v[216:219], v[66:69]
	v_mfma_f32_16x16x32_bf16 v[58:61], v[184:187], v[212:215], v[58:61]
	v_mfma_f32_16x16x32_bf16 v[58:61], v[188:191], v[216:219], v[58:61]
	v_mfma_f32_16x16x32_bf16 v[50:53], v[176:179], v[220:223], v[50:53]
	v_mfma_f32_16x16x32_bf16 v[50:53], v[180:183], v[224:227], v[50:53]
	v_mfma_f32_16x16x32_bf16 v[42:45], v[184:187], v[220:223], v[42:45]
	v_mfma_f32_16x16x32_bf16 v[42:45], v[188:191], v[224:227], v[42:45]
	v_mfma_f32_16x16x32_bf16 v[34:37], v[176:179], v[228:231], v[34:37]
	v_mfma_f32_16x16x32_bf16 v[34:37], v[180:183], v[232:235], v[34:37]
	v_mfma_f32_16x16x32_bf16 v[26:29], v[184:187], v[228:231], v[26:29]
	v_mfma_f32_16x16x32_bf16 v[26:29], v[188:191], v[232:235], v[26:29]
	v_mfma_f32_16x16x32_bf16 v[18:21], v[176:179], v[236:239], v[18:21]
	v_mfma_f32_16x16x32_bf16 v[18:21], v[180:183], v[240:243], v[18:21]
	v_mfma_f32_16x16x32_bf16 v[10:13], v[184:187], v[236:239], v[10:13]
	v_mfma_f32_16x16x32_bf16 v[10:13], v[188:191], v[240:243], v[10:13]
	s_barrier
	s_add_i32 s4, 0, 0x18000
	v_add_u32_e32 v158, s4, v155
	s_add_i32 s5, 0, 0x1c000
	ds_read_b128 v[144:147], v158
	ds_read_b128 v[148:151], v158 offset:1024
	ds_read_b128 v[168:171], v158 offset:2048
	ds_read_b128 v[172:175], v158 offset:3072
	v_add_u32_e32 v158, s5, v155
	ds_read_b128 v[176:179], v158
	ds_read_b128 v[180:183], v158 offset:1024
	ds_read_b128 v[184:187], v158 offset:2048
	ds_read_b128 v[188:191], v158 offset:3072
	s_add_u32 s34, s56, 0x80000
	s_addc_u32 s35, s57, 0
	s_mov_b32 m0, s60
	v_lshl_add_u64 v[248:249], s[34:35], 0, v[136:137]
	ds_read_b128 v[212:215], v157 offset:32768
	ds_read_b128 v[216:219], v157 offset:33792
	ds_read_b128 v[220:223], v157 offset:34816
	ds_read_b128 v[224:227], v157 offset:35840
	ds_read_b128 v[228:231], v157 offset:36864
	ds_read_b128 v[232:235], v157 offset:37888
	ds_read_b128 v[236:239], v157 offset:38912
	ds_read_b128 v[240:243], v157 offset:39936
	global_load_lds_dwordx4 v[248:249], off
	v_lshl_add_u64 v[248:249], s[34:35], 0, v[134:135]
	s_mov_b32 m0, s2
	s_nop 0
	global_load_lds_dwordx4 v[248:249], off
	s_waitcnt vmcnt(8)
	s_waitcnt lgkmcnt(0)
	s_barrier
	v_mfma_f32_16x16x32_bf16 v[126:129], v[144:147], v[212:215], v[126:129]
	v_mfma_f32_16x16x32_bf16 v[126:129], v[148:151], v[216:219], v[126:129]
	v_mfma_f32_16x16x32_bf16 v[118:121], v[168:171], v[212:215], v[118:121]
	v_mfma_f32_16x16x32_bf16 v[118:121], v[172:175], v[216:219], v[118:121]
	v_mfma_f32_16x16x32_bf16 v[110:113], v[144:147], v[220:223], v[110:113]
	v_mfma_f32_16x16x32_bf16 v[110:113], v[148:151], v[224:227], v[110:113]
	v_mfma_f32_16x16x32_bf16 v[102:105], v[168:171], v[220:223], v[102:105]
	v_mfma_f32_16x16x32_bf16 v[102:105], v[172:175], v[224:227], v[102:105]
	v_mfma_f32_16x16x32_bf16 v[94:97], v[144:147], v[228:231], v[94:97]
	v_mfma_f32_16x16x32_bf16 v[94:97], v[148:151], v[232:235], v[94:97]
	v_mfma_f32_16x16x32_bf16 v[86:89], v[168:171], v[228:231], v[86:89]
	v_mfma_f32_16x16x32_bf16 v[86:89], v[172:175], v[232:235], v[86:89]
	v_mfma_f32_16x16x32_bf16 v[78:81], v[144:147], v[236:239], v[78:81]
	v_mfma_f32_16x16x32_bf16 v[78:81], v[148:151], v[240:243], v[78:81]
	v_mfma_f32_16x16x32_bf16 v[70:73], v[168:171], v[236:239], v[70:73]
	v_mfma_f32_16x16x32_bf16 v[70:73], v[172:175], v[240:243], v[70:73]
	v_mfma_f32_16x16x32_bf16 v[130:133], v[176:179], v[212:215], v[130:133]
	v_mfma_f32_16x16x32_bf16 v[130:133], v[180:183], v[216:219], v[130:133]
	v_mfma_f32_16x16x32_bf16 v[122:125], v[184:187], v[212:215], v[122:125]
	v_mfma_f32_16x16x32_bf16 v[122:125], v[188:191], v[216:219], v[122:125]
	v_mfma_f32_16x16x32_bf16 v[114:117], v[176:179], v[220:223], v[114:117]
	v_mfma_f32_16x16x32_bf16 v[114:117], v[180:183], v[224:227], v[114:117]
	v_mfma_f32_16x16x32_bf16 v[106:109], v[184:187], v[220:223], v[106:109]
	v_mfma_f32_16x16x32_bf16 v[106:109], v[188:191], v[224:227], v[106:109]
	v_mfma_f32_16x16x32_bf16 v[98:101], v[176:179], v[228:231], v[98:101]
	v_mfma_f32_16x16x32_bf16 v[98:101], v[180:183], v[232:235], v[98:101]
	v_mfma_f32_16x16x32_bf16 v[90:93], v[184:187], v[228:231], v[90:93]
	v_mfma_f32_16x16x32_bf16 v[90:93], v[188:191], v[232:235], v[90:93]
	v_mfma_f32_16x16x32_bf16 v[82:85], v[176:179], v[236:239], v[82:85]
	v_mfma_f32_16x16x32_bf16 v[82:85], v[180:183], v[240:243], v[82:85]
	v_mfma_f32_16x16x32_bf16 v[74:77], v[184:187], v[236:239], v[74:77]
	v_mfma_f32_16x16x32_bf16 v[74:77], v[188:191], v[240:243], v[74:77]
	s_barrier
; #define PG8_STAGE(bufoff, gbase, voff) do { _Pragma("unroll") for (int _i = 0; _i < 2; ++_i) \
;         __builtin_amdgcn_global_load_lds((const unsigned*)((const char*)(gbase) + (voff)[_i]), (PG8_LAS unsigned*)(lds + (bufoff) + ldsw + _i * 8192), 16, 0, 0); } while (0)
; #define PG8_LDA(dst, b, h) do { _Pragma("unroll") for (int m = 0; m < 4; ++m) _Pragma("unroll") for (int k = 0; k < 2; ++k) dst[m][k] = *(const PG8_LAS bf16x8*)(lds + PG8_SA(b, h) + aoff + m * 2048 + k * 1024); } while (0)
; #define PG8_MMA(ai, bj, At, Bt) do { __builtin_amdgcn_s_setprio(1); _Pragma("unroll") for (int m = 0; m < 4; ++m) _Pragma("unroll") for (int n = 0; n < 2; ++n) _Pragma("unroll") for (int k = 0; k < 2; ++k) \
;         acc[ai][bj][m][n] = __builtin_amdgcn_mfma_f32_16x16x32_bf16(Bt[n][k], At[m][k], acc[ai][bj][m][n], 0, 0, 0); __builtin_amdgcn_s_setprio(0); } while (0)
; #define PG8_WAIT_V(n) asm volatile("s_waitcnt vmcnt(" #n ")" ::: "memory")
; #define PG8_WAIT_L(n) asm volatile("s_waitcnt lgkmcnt(" #n ")" ::: "memory")
; #define PG8_BAR __builtin_amdgcn_s_barrier()
; #define PG8_SCHED __builtin_amdgcn_sched_barrier(0)
; template <class Epi, class Sched, bool ALIGN_EPI = false, bool SP2 = false>
; __device__ __forceinline__ void gemm_phase(PG8_LAS unsigned char* lds, const Gemm g, const Sched& S, const Epi& E) {
;     ...
;         for (int t = 0; t < nt; t += 2) {
;     ...
;             PG8_LDA(At, 1, 1); PG8_STAGE(PG8_SB(1, 0), b3, voffB); PG8_STAGE(PG8_SB(1, 1), b3 + hstep, voffB); PG8_STAGE(PG8_SA(1, 0), a3, voffA);
;             PG8_WAIT_V(8); PG8_WAIT_L(0); PG8_BAR; PG8_MMA(1, 0, At, B0); PG8_MMA(1, 1, At, B1); PG8_BAR; PG8_SCHED;
	s_add_i32 s4, s4, s65
	v_lshl_add_u64 v[152:153], v[152:153], 0, s[28:29]
	s_mov_b32 m0, s4
	ds_read_b128 v[212:215], v157 offset:49152
	ds_read_b128 v[216:219], v157 offset:50176
	ds_read_b128 v[220:223], v157 offset:51200
	ds_read_b128 v[224:227], v157 offset:52224
	ds_read_b128 v[228:231], v157 offset:53248
	ds_read_b128 v[232:235], v157 offset:54272
	ds_read_b128 v[236:239], v157 offset:55296
	ds_read_b128 v[240:243], v157 offset:56320
	global_load_lds_dwordx4 v[152:153], off
	s_add_i32 m0, s4, 0x2000
	s_add_u32 s22, s22, 0x80080
	v_lshl_add_u64 v[152:153], v[192:193], 0, s[28:29]
	s_addc_u32 s23, s23, 0
	s_add_i32 s4, s5, s65
	global_load_lds_dwordx4 v[152:153], off
	v_lshl_add_u64 v[152:153], s[22:23], 0, v[4:5]
	s_mov_b32 m0, s4
	s_nop 0
	global_load_lds_dwordx4 v[152:153], off
	v_lshl_add_u64 v[152:153], s[22:23], 0, v[2:3]
	s_add_i32 m0, s4, 0x2000
	s_nop 0
	global_load_lds_dwordx4 v[152:153], off
	v_lshl_add_u64 v[152:153], v[244:245], 0, s[28:29]
	s_mov_b32 m0, s3
	s_nop 0
	global_load_lds_dwordx4 v[152:153], off
	v_lshl_add_u64 v[152:153], v[246:247], 0, s[28:29]
	s_mov_b32 m0, s75
	s_nop 0
	global_load_lds_dwordx4 v[152:153], off
	s_waitcnt vmcnt(8)
	s_waitcnt lgkmcnt(0)
	s_barrier
	v_mfma_f32_16x16x32_bf16 v[62:65], v[144:147], v[212:215], v[62:65]
	v_mfma_f32_16x16x32_bf16 v[62:65], v[148:151], v[216:219], v[62:65]
	v_mfma_f32_16x16x32_bf16 v[54:57], v[168:171], v[212:215], v[54:57]
	v_mfma_f32_16x16x32_bf16 v[54:57], v[172:175], v[216:219], v[54:57]
	v_mfma_f32_16x16x32_bf16 v[46:49], v[144:147], v[220:223], v[46:49]
	v_mfma_f32_16x16x32_bf16 v[46:49], v[148:151], v[224:227], v[46:49]
	v_mfma_f32_16x16x32_bf16 v[38:41], v[168:171], v[220:223], v[38:41]
	v_mfma_f32_16x16x32_bf16 v[38:41], v[172:175], v[224:227], v[38:41]
	v_mfma_f32_16x16x32_bf16 v[30:33], v[144:147], v[228:231], v[30:33]
	v_mfma_f32_16x16x32_bf16 v[30:33], v[148:151], v[232:235], v[30:33]
	v_mfma_f32_16x16x32_bf16 v[22:25], v[168:171], v[228:231], v[22:25]
	v_mfma_f32_16x16x32_bf16 v[22:25], v[172:175], v[232:235], v[22:25]
	v_mfma_f32_16x16x32_bf16 v[14:17], v[144:147], v[236:239], v[14:17]
	v_mfma_f32_16x16x32_bf16 v[14:17], v[148:151], v[240:243], v[14:17]
	v_mfma_f32_16x16x32_bf16 v[6:9], v[168:171], v[236:239], v[6:9]
	v_mfma_f32_16x16x32_bf16 v[6:9], v[172:175], v[240:243], v[6:9]
	v_mfma_f32_16x16x32_bf16 v[66:69], v[176:179], v[212:215], v[66:69]
	v_mfma_f32_16x16x32_bf16 v[66:69], v[180:183], v[216:219], v[66:69]
	v_mfma_f32_16x16x32_bf16 v[58:61], v[184:187], v[212:215], v[58:61]
	v_mfma_f32_16x16x32_bf16 v[58:61], v[188:191], v[216:219], v[58:61]
	v_mfma_f32_16x16x32_bf16 v[50:53], v[176:179], v[220:223], v[50:53]
	v_mfma_f32_16x16x32_bf16 v[50:53], v[180:183], v[224:227], v[50:53]
	v_mfma_f32_16x16x32_bf16 v[42:45], v[184:187], v[220:223], v[42:45]
	v_mfma_f32_16x16x32_bf16 v[42:45], v[188:191], v[224:227], v[42:45]
	v_mfma_f32_16x16x32_bf16 v[34:37], v[176:179], v[228:231], v[34:37]
	v_mfma_f32_16x16x32_bf16 v[34:37], v[180:183], v[232:235], v[34:37]
	v_mfma_f32_16x16x32_bf16 v[26:29], v[184:187], v[228:231], v[26:29]
	v_mfma_f32_16x16x32_bf16 v[26:29], v[188:191], v[232:235], v[26:29]
	v_mfma_f32_16x16x32_bf16 v[18:21], v[176:179], v[236:239], v[18:21]
	v_mfma_f32_16x16x32_bf16 v[18:21], v[180:183], v[240:243], v[18:21]
	v_mfma_f32_16x16x32_bf16 v[10:13], v[184:187], v[236:239], v[10:13]
	v_mfma_f32_16x16x32_bf16 v[10:13], v[188:191], v[240:243], v[10:13]
	s_barrier
	s_add_i32 s20, s20, 2
	s_add_u32 s54, s54, 0x100
	s_addc_u32 s55, s55, 0
	s_add_u32 s71, s71, 0x100
	s_addc_u32 s77, s77, 0
	s_cmp_gt_u32 s20, 29
	s_cbranch_scc0 .LBB0_216
	s_and_b64 vcc, exec, s[44:45]
	s_movk_i32 s77, 0x6000
	s_mov_b32 s71, 0x44800000
	s_cbranch_vccz .LBB0_219
	s_barrier

; #define PG8_STAGE(bufoff, gbase, voff) do { _Pragma("unroll") for (int _i = 0; _i < 2; ++_i) \
;         __builtin_amdgcn_global_load_lds((const unsigned*)((const char*)(gbase) + (voff)[_i]), (PG8_LAS unsigned*)(lds + (bufoff) + ldsw + _i * 8192), 16, 0, 0); } while (0)
; #define PG8_LDA(dst, b, h) do { _Pragma("unroll") for (int m = 0; m < 4; ++m) _Pragma("unroll") for (int k = 0; k < 2; ++k) dst[m][k] = *(const PG8_LAS bf16x8*)(lds + PG8_SA(b, h) + aoff + m * 2048 + k * 1024); } while (0)
; #define PG8_LDB(dst, b, h) do { _Pragma("unroll") for (int n = 0; n < 2; ++n) _Pragma("unroll") for (int k = 0; k < 2; ++k) dst[n][k] = *(const PG8_LAS bf16x8*)(lds + PG8_SB(b, h) + boff + n * 2048 + k * 1024); } while (0)
; #define PG8_MMA(ai, bj, At, Bt) do { __builtin_amdgcn_s_setprio(1); _Pragma("unroll") for (int m = 0; m < 4; ++m) _Pragma("unroll") for (int n = 0; n < 2; ++n) _Pragma("unroll") for (int k = 0; k < 2; ++k) \
;         acc[ai][bj][m][n] = __builtin_amdgcn_mfma_f32_16x16x32_bf16(Bt[n][k], At[m][k], acc[ai][bj][m][n], 0, 0, 0); __builtin_amdgcn_s_setprio(0); } while (0)
; #define PG8_WAIT_V(n) asm volatile("s_waitcnt vmcnt(" #n ")" ::: "memory")
; #define PG8_WAIT_L(n) asm volatile("s_waitcnt lgkmcnt(" #n ")" ::: "memory")
; #define PG8_BAR __builtin_amdgcn_s_barrier()
; #define PG8_SCHED __builtin_amdgcn_sched_barrier(0)
; template <class Epi, class Sched, bool ALIGN_EPI = false, bool SP2 = false>
; __device__ __forceinline__ void gemm_phase(PG8_LAS unsigned char* lds, const Gemm g, const Sched& S, const Epi& E) {
;     ...
;             const bool last = (t == nt - 2);
;             const char* a1 = cA + (size_t)(t + 1) * kstep;
;             const char* a2 = last ? nA : cA + (size_t)(t + 2) * kstep; const char* b2 = last ? nB : cB + (size_t)(t + 2) * kstep;
;             const char* a3 = a2 + kstep; const char* b3 = b2 + kstep;
;             if (last && has_next) S.a_ready(nxt);
;             if constexpr (SP2) {
;             PG8_LDB(B0, 0, 0); PG8_LDB(B1, 0, 1); PG8_SCHED; PG8_LDA(At, 0, 0); PG8_STAGE(PG8_SA(1, 1), a1 + hstep, voffA);
;             PG8_WAIT_V(8); PG8_WAIT_L(0); PG8_BAR; PG8_MMA(0, 0, At, B0); PG8_MMA(0, 1, At, B1); PG8_BAR; PG8_SCHED;
;             PG8_LDA(At, 0, 1); PG8_STAGE(PG8_SB(0, 0), b2, voffB); PG8_STAGE(PG8_SB(0, 1), b2 + hstep, voffB); PG8_STAGE(PG8_SA(0, 0), a2, voffA);
.LBB0_299:
	s_add_u32 s50, s22, 0x100
	s_addc_u32 s51, s23, 0
	s_add_i32 s4, 0, 0x10000
	s_cmpk_eq_i32 s20, 0x54
	s_cselect_b32 s55, s41, s51
	s_cselect_b32 s54, s40, s50
	s_cselect_b32 s53, s49, s69
	s_cselect_b32 s52, s48, s33
	s_add_i32 s5, 0, 0x14000
	v_add_u32_e32 v146, s4, v158
	v_add_u32_e32 v180, s5, v158
	ds_read_b128 v[134:137], v146
	ds_read_b128 v[138:141], v146 offset:1024
	ds_read_b128 v[142:145], v146 offset:2048
	ds_read_b128 v[146:149], v146 offset:3072
	ds_read_b128 v[150:153], v180
	ds_read_b128 v[154:157], v180 offset:1024
	ds_read_b128 v[176:179], v180 offset:2048
	ds_read_b128 v[180:183], v180 offset:3072
	v_lshl_add_u64 v[236:237], s[22:23], 0, v[172:173]
	s_add_i32 m0, s56, 0xc000
	ds_read_b128 v[184:187], v188
	ds_read_b128 v[190:193], v188 offset:1024
	ds_read_b128 v[212:215], v188 offset:2048
	ds_read_b128 v[216:219], v188 offset:3072
	ds_read_b128 v[220:223], v188 offset:4096
	ds_read_b128 v[224:227], v188 offset:5120
	ds_read_b128 v[228:231], v188 offset:6144
	ds_read_b128 v[232:235], v188 offset:7168
	global_load_lds_dwordx4 v[236:237], off
	v_lshl_add_u64 v[236:237], s[22:23], 0, v[174:175]
	s_add_i32 m0, s56, 0xe000
	s_nop 0
	global_load_lds_dwordx4 v[236:237], off
	s_waitcnt vmcnt(8)
	s_waitcnt lgkmcnt(0)
	s_barrier
	v_mfma_f32_16x16x32_bf16 v[122:125], v[134:137], v[184:187], v[122:125]
	v_mfma_f32_16x16x32_bf16 v[122:125], v[138:141], v[190:193], v[122:125]
	v_mfma_f32_16x16x32_bf16 v[118:121], v[142:145], v[184:187], v[118:121]
	v_mfma_f32_16x16x32_bf16 v[118:121], v[146:149], v[190:193], v[118:121]
	v_mfma_f32_16x16x32_bf16 v[114:117], v[134:137], v[212:215], v[114:117]
	v_mfma_f32_16x16x32_bf16 v[114:117], v[138:141], v[216:219], v[114:117]
	v_mfma_f32_16x16x32_bf16 v[110:113], v[142:145], v[212:215], v[110:113]
	v_mfma_f32_16x16x32_bf16 v[110:113], v[146:149], v[216:219], v[110:113]
	v_mfma_f32_16x16x32_bf16 v[98:101], v[134:137], v[220:223], v[98:101]
	v_mfma_f32_16x16x32_bf16 v[98:101], v[138:141], v[224:227], v[98:101]
	v_mfma_f32_16x16x32_bf16 v[94:97], v[142:145], v[220:223], v[94:97]
	v_mfma_f32_16x16x32_bf16 v[94:97], v[146:149], v[224:227], v[94:97]
	v_mfma_f32_16x16x32_bf16 v[82:85], v[134:137], v[228:231], v[82:85]
	v_mfma_f32_16x16x32_bf16 v[82:85], v[138:141], v[232:235], v[82:85]
	v_mfma_f32_16x16x32_bf16 v[78:81], v[142:145], v[228:231], v[78:81]
	v_mfma_f32_16x16x32_bf16 v[78:81], v[146:149], v[232:235], v[78:81]
	v_mfma_f32_16x16x32_bf16 v[130:133], v[150:153], v[184:187], v[130:133]
	v_mfma_f32_16x16x32_bf16 v[130:133], v[154:157], v[190:193], v[130:133]
	v_mfma_f32_16x16x32_bf16 v[126:129], v[176:179], v[184:187], v[126:129]
	v_mfma_f32_16x16x32_bf16 v[126:129], v[180:183], v[190:193], v[126:129]
	v_mfma_f32_16x16x32_bf16 v[106:109], v[150:153], v[212:215], v[106:109]
	v_mfma_f32_16x16x32_bf16 v[106:109], v[154:157], v[216:219], v[106:109]
	v_mfma_f32_16x16x32_bf16 v[102:105], v[176:179], v[212:215], v[102:105]
	v_mfma_f32_16x16x32_bf16 v[102:105], v[180:183], v[216:219], v[102:105]
	v_mfma_f32_16x16x32_bf16 v[90:93], v[150:153], v[220:223], v[90:93]
	v_mfma_f32_16x16x32_bf16 v[90:93], v[154:157], v[224:227], v[90:93]
	v_mfma_f32_16x16x32_bf16 v[86:89], v[176:179], v[220:223], v[86:89]
	v_mfma_f32_16x16x32_bf16 v[86:89], v[180:183], v[224:227], v[86:89]
	v_mfma_f32_16x16x32_bf16 v[74:77], v[150:153], v[228:231], v[74:77]
	v_mfma_f32_16x16x32_bf16 v[74:77], v[154:157], v[232:235], v[74:77]
	v_mfma_f32_16x16x32_bf16 v[70:73], v[176:179], v[228:231], v[70:73]
	v_mfma_f32_16x16x32_bf16 v[70:73], v[180:183], v[232:235], v[70:73]
	s_barrier
	s_add_i32 s4, s4, s24
	v_lshl_add_u64 v[236:237], s[52:53], 0, v[4:5]
	s_mov_b32 m0, s4
	ds_read_b128 v[184:187], v188 offset:16384
	ds_read_b128 v[190:193], v188 offset:17408
	ds_read_b128 v[212:215], v188 offset:18432
	ds_read_b128 v[216:219], v188 offset:19456
	ds_read_b128 v[220:223], v188 offset:20480
	ds_read_b128 v[224:227], v188 offset:21504
	ds_read_b128 v[228:231], v188 offset:22528
	ds_read_b128 v[232:235], v188 offset:23552
	global_load_lds_dwordx4 v[236:237], off
	s_add_i32 m0, s4, 0x2000
	s_add_u32 s22, s52, 0x160000
	v_lshl_add_u64 v[238:239], s[52:53], 0, v[170:171]
	s_addc_u32 s23, s53, 0
	s_add_i32 s4, s5, s24
	global_load_lds_dwordx4 v[238:239], off
	v_lshl_add_u64 v[240:241], s[22:23], 0, v[4:5]
	s_mov_b32 m0, s4
	v_lshl_add_u64 v[242:243], s[54:55], 0, v[168:169]
	global_load_lds_dwordx4 v[240:241], off
	v_lshl_add_u64 v[240:241], s[22:23], 0, v[170:171]
	s_add_i32 m0, s4, 0x2000
	s_nop 0
	global_load_lds_dwordx4 v[240:241], off
	v_lshl_add_u64 v[240:241], s[54:55], 0, v[2:3]
	s_mov_b32 m0, s56
	s_nop 0
	global_load_lds_dwordx4 v[240:241], off
	s_mov_b32 m0, s57
	s_nop 0
	global_load_lds_dwordx4 v[242:243], off
	s_waitcnt vmcnt(8)
	s_waitcnt lgkmcnt(0)
	s_barrier
; #define PG8_STAGE(bufoff, gbase, voff) do { _Pragma("unroll") for (int _i = 0; _i < 2; ++_i) \
;         __builtin_amdgcn_global_load_lds((const unsigned*)((const char*)(gbase) + (voff)[_i]), (PG8_LAS unsigned*)(lds + (bufoff) + ldsw + _i * 8192), 16, 0, 0); } while (0)
; #define PG8_LDA(dst, b, h) do { _Pragma("unroll") for (int m = 0; m < 4; ++m) _Pragma("unroll") for (int k = 0; k < 2; ++k) dst[m][k] = *(const PG8_LAS bf16x8*)(lds + PG8_SA(b, h) + aoff + m * 2048 + k * 1024); } while (0)
; #define PG8_LDB(dst, b, h) do { _Pragma("unroll") for (int n = 0; n < 2; ++n) _Pragma("unroll") for (int k = 0; k < 2; ++k) dst[n][k] = *(const PG8_LAS bf16x8*)(lds + PG8_SB(b, h) + boff + n * 2048 + k * 1024); } while (0)
; #define PG8_MMA(ai, bj, At, Bt) do { __builtin_amdgcn_s_setprio(1); _Pragma("unroll") for (int m = 0; m < 4; ++m) _Pragma("unroll") for (int n = 0; n < 2; ++n) _Pragma("unroll") for (int k = 0; k < 2; ++k) \
;         acc[ai][bj][m][n] = __builtin_amdgcn_mfma_f32_16x16x32_bf16(Bt[n][k], At[m][k], acc[ai][bj][m][n], 0, 0, 0); __builtin_amdgcn_s_setprio(0); } while (0)
; #define PG8_WAIT_V(n) asm volatile("s_waitcnt vmcnt(" #n ")" ::: "memory")
; #define PG8_WAIT_L(n) asm volatile("s_waitcnt lgkmcnt(" #n ")" ::: "memory")
; #define PG8_BAR __builtin_amdgcn_s_barrier()
; #define PG8_SCHED __builtin_amdgcn_sched_barrier(0)
; template <class Epi, class Sched, bool ALIGN_EPI = false, bool SP2 = false>
; __device__ __forceinline__ void gemm_phase(PG8_LAS unsigned char* lds, const Gemm g, const Sched& S, const Epi& E) {
;     ...
;             PG8_WAIT_V(8); PG8_WAIT_L(0); PG8_BAR; PG8_MMA(1, 0, At, B0); PG8_MMA(1, 1, At, B1); PG8_BAR; PG8_SCHED;
;             PG8_LDB(B0, 1, 0); PG8_LDB(B1, 1, 1); PG8_SCHED; PG8_LDA(At, 1, 0); PG8_STAGE(PG8_SA(0, 1), a2 + hstep, voffA);
;             PG8_WAIT_V(8); PG8_WAIT_L(0); PG8_BAR; PG8_MMA(0, 0, At, B0); PG8_MMA(0, 1, At, B1); PG8_BAR; PG8_SCHED;
	v_mfma_f32_16x16x32_bf16 v[58:61], v[134:137], v[184:187], v[58:61]
	v_mfma_f32_16x16x32_bf16 v[58:61], v[138:141], v[190:193], v[58:61]
	v_mfma_f32_16x16x32_bf16 v[54:57], v[142:145], v[184:187], v[54:57]
	v_mfma_f32_16x16x32_bf16 v[54:57], v[146:149], v[190:193], v[54:57]
	v_mfma_f32_16x16x32_bf16 v[50:53], v[134:137], v[212:215], v[50:53]
	v_mfma_f32_16x16x32_bf16 v[50:53], v[138:141], v[216:219], v[50:53]
	v_mfma_f32_16x16x32_bf16 v[46:49], v[142:145], v[212:215], v[46:49]
	v_mfma_f32_16x16x32_bf16 v[46:49], v[146:149], v[216:219], v[46:49]
	v_mfma_f32_16x16x32_bf16 v[34:37], v[134:137], v[220:223], v[34:37]
	v_mfma_f32_16x16x32_bf16 v[34:37], v[138:141], v[224:227], v[34:37]
	v_mfma_f32_16x16x32_bf16 v[30:33], v[142:145], v[220:223], v[30:33]
	v_mfma_f32_16x16x32_bf16 v[30:33], v[146:149], v[224:227], v[30:33]
	v_mfma_f32_16x16x32_bf16 v[18:21], v[134:137], v[228:231], v[18:21]
	v_mfma_f32_16x16x32_bf16 v[18:21], v[138:141], v[232:235], v[18:21]
	v_mfma_f32_16x16x32_bf16 v[14:17], v[142:145], v[228:231], v[14:17]
	v_mfma_f32_16x16x32_bf16 v[14:17], v[146:149], v[232:235], v[14:17]
	v_mfma_f32_16x16x32_bf16 v[66:69], v[150:153], v[184:187], v[66:69]
	v_mfma_f32_16x16x32_bf16 v[66:69], v[154:157], v[190:193], v[66:69]
	v_mfma_f32_16x16x32_bf16 v[62:65], v[176:179], v[184:187], v[62:65]
	v_mfma_f32_16x16x32_bf16 v[62:65], v[180:183], v[190:193], v[62:65]
	v_mfma_f32_16x16x32_bf16 v[42:45], v[150:153], v[212:215], v[42:45]
	v_mfma_f32_16x16x32_bf16 v[42:45], v[154:157], v[216:219], v[42:45]
	v_mfma_f32_16x16x32_bf16 v[38:41], v[176:179], v[212:215], v[38:41]
	v_mfma_f32_16x16x32_bf16 v[38:41], v[180:183], v[216:219], v[38:41]
	v_mfma_f32_16x16x32_bf16 v[26:29], v[150:153], v[220:223], v[26:29]
	v_mfma_f32_16x16x32_bf16 v[26:29], v[154:157], v[224:227], v[26:29]
	v_mfma_f32_16x16x32_bf16 v[22:25], v[176:179], v[220:223], v[22:25]
	v_mfma_f32_16x16x32_bf16 v[22:25], v[180:183], v[224:227], v[22:25]
	v_mfma_f32_16x16x32_bf16 v[10:13], v[150:153], v[228:231], v[10:13]
	v_mfma_f32_16x16x32_bf16 v[10:13], v[154:157], v[232:235], v[10:13]
	v_mfma_f32_16x16x32_bf16 v[6:9], v[176:179], v[228:231], v[6:9]
	v_mfma_f32_16x16x32_bf16 v[6:9], v[180:183], v[232:235], v[6:9]
	s_barrier
	s_add_i32 s4, 0, 0x18000
	s_add_i32 s5, 0, 0x1c000
	v_add_u32_e32 v146, s4, v158
	v_add_u32_e32 v180, s5, v158
	ds_read_b128 v[134:137], v146
	ds_read_b128 v[138:141], v146 offset:1024
	ds_read_b128 v[142:145], v146 offset:2048
	ds_read_b128 v[146:149], v146 offset:3072
	ds_read_b128 v[150:153], v180
	ds_read_b128 v[154:157], v180 offset:1024
	ds_read_b128 v[176:179], v180 offset:2048
	ds_read_b128 v[180:183], v180 offset:3072
	s_add_u32 s22, s54, 0x160000
	s_addc_u32 s23, s55, 0
	s_mov_b32 m0, s59
	v_lshl_add_u64 v[244:245], s[22:23], 0, v[2:3]
	ds_read_b128 v[184:187], v188 offset:32768
	ds_read_b128 v[190:193], v188 offset:33792
	ds_read_b128 v[212:215], v188 offset:34816
	ds_read_b128 v[216:219], v188 offset:35840
	ds_read_b128 v[220:223], v188 offset:36864
	ds_read_b128 v[224:227], v188 offset:37888
	ds_read_b128 v[228:231], v188 offset:38912
	ds_read_b128 v[232:235], v188 offset:39936
	global_load_lds_dwordx4 v[244:245], off
	v_lshl_add_u64 v[244:245], s[22:23], 0, v[168:169]
	s_mov_b32 m0, s60
	s_nop 0
	global_load_lds_dwordx4 v[244:245], off
	s_waitcnt vmcnt(8)
	s_waitcnt lgkmcnt(0)
	s_barrier
	v_mfma_f32_16x16x32_bf16 v[122:125], v[134:137], v[184:187], v[122:125]
	v_mfma_f32_16x16x32_bf16 v[122:125], v[138:141], v[190:193], v[122:125]
	v_mfma_f32_16x16x32_bf16 v[118:121], v[142:145], v[184:187], v[118:121]
	v_mfma_f32_16x16x32_bf16 v[118:121], v[146:149], v[190:193], v[118:121]
	v_mfma_f32_16x16x32_bf16 v[114:117], v[134:137], v[212:215], v[114:117]
	v_mfma_f32_16x16x32_bf16 v[114:117], v[138:141], v[216:219], v[114:117]
	v_mfma_f32_16x16x32_bf16 v[110:113], v[142:145], v[212:215], v[110:113]
	v_mfma_f32_16x16x32_bf16 v[110:113], v[146:149], v[216:219], v[110:113]
	v_mfma_f32_16x16x32_bf16 v[98:101], v[134:137], v[220:223], v[98:101]
	v_mfma_f32_16x16x32_bf16 v[98:101], v[138:141], v[224:227], v[98:101]
	v_mfma_f32_16x16x32_bf16 v[94:97], v[142:145], v[220:223], v[94:97]
	v_mfma_f32_16x16x32_bf16 v[94:97], v[146:149], v[224:227], v[94:97]
	v_mfma_f32_16x16x32_bf16 v[82:85], v[134:137], v[228:231], v[82:85]
	v_mfma_f32_16x16x32_bf16 v[82:85], v[138:141], v[232:235], v[82:85]
	v_mfma_f32_16x16x32_bf16 v[78:81], v[142:145], v[228:231], v[78:81]
	v_mfma_f32_16x16x32_bf16 v[78:81], v[146:149], v[232:235], v[78:81]
	v_mfma_f32_16x16x32_bf16 v[130:133], v[150:153], v[184:187], v[130:133]
	v_mfma_f32_16x16x32_bf16 v[130:133], v[154:157], v[190:193], v[130:133]
	v_mfma_f32_16x16x32_bf16 v[126:129], v[176:179], v[184:187], v[126:129]
	v_mfma_f32_16x16x32_bf16 v[126:129], v[180:183], v[190:193], v[126:129]
	v_mfma_f32_16x16x32_bf16 v[106:109], v[150:153], v[212:215], v[106:109]
	v_mfma_f32_16x16x32_bf16 v[106:109], v[154:157], v[216:219], v[106:109]
	v_mfma_f32_16x16x32_bf16 v[102:105], v[176:179], v[212:215], v[102:105]
	v_mfma_f32_16x16x32_bf16 v[102:105], v[180:183], v[216:219], v[102:105]
	v_mfma_f32_16x16x32_bf16 v[90:93], v[150:153], v[220:223], v[90:93]
	v_mfma_f32_16x16x32_bf16 v[90:93], v[154:157], v[224:227], v[90:93]
	v_mfma_f32_16x16x32_bf16 v[86:89], v[176:179], v[220:223], v[86:89]
	v_mfma_f32_16x16x32_bf16 v[86:89], v[180:183], v[224:227], v[86:89]
	v_mfma_f32_16x16x32_bf16 v[74:77], v[150:153], v[228:231], v[74:77]
	v_mfma_f32_16x16x32_bf16 v[74:77], v[154:157], v[232:235], v[74:77]
	v_mfma_f32_16x16x32_bf16 v[70:73], v[176:179], v[228:231], v[70:73]
	v_mfma_f32_16x16x32_bf16 v[70:73], v[180:183], v[232:235], v[70:73]
	s_barrier
; #define PG8_STAGE(bufoff, gbase, voff) do { _Pragma("unroll") for (int _i = 0; _i < 2; ++_i) \
;         __builtin_amdgcn_global_load_lds((const unsigned*)((const char*)(gbase) + (voff)[_i]), (PG8_LAS unsigned*)(lds + (bufoff) + ldsw + _i * 8192), 16, 0, 0); } while (0)
; #define PG8_LDA(dst, b, h) do { _Pragma("unroll") for (int m = 0; m < 4; ++m) _Pragma("unroll") for (int k = 0; k < 2; ++k) dst[m][k] = *(const PG8_LAS bf16x8*)(lds + PG8_SA(b, h) + aoff + m * 2048 + k * 1024); } while (0)
; #define PG8_MMA(ai, bj, At, Bt) do { __builtin_amdgcn_s_setprio(1); _Pragma("unroll") for (int m = 0; m < 4; ++m) _Pragma("unroll") for (int n = 0; n < 2; ++n) _Pragma("unroll") for (int k = 0; k < 2; ++k) \
;         acc[ai][bj][m][n] = __builtin_amdgcn_mfma_f32_16x16x32_bf16(Bt[n][k], At[m][k], acc[ai][bj][m][n], 0, 0, 0); __builtin_amdgcn_s_setprio(0); } while (0)
; #define PG8_WAIT_V(n) asm volatile("s_waitcnt vmcnt(" #n ")" ::: "memory")
; #define PG8_WAIT_L(n) asm volatile("s_waitcnt lgkmcnt(" #n ")" ::: "memory")
; #define PG8_BAR __builtin_amdgcn_s_barrier()
; #define PG8_SCHED __builtin_amdgcn_sched_barrier(0)
; template <class Epi, class Sched, bool ALIGN_EPI = false, bool SP2 = false>
; __device__ __forceinline__ void gemm_phase(PG8_LAS unsigned char* lds, const Gemm g, const Sched& S, const Epi& E) {
;     ...
;         for (int t = 0; t < nt; t += 2) {
;     ...
;             PG8_LDA(At, 1, 1); PG8_STAGE(PG8_SB(1, 0), b3, voffB); PG8_STAGE(PG8_SB(1, 1), b3 + hstep, voffB); PG8_STAGE(PG8_SA(1, 0), a3, voffA);
;             PG8_WAIT_V(8); PG8_WAIT_L(0); PG8_BAR; PG8_MMA(1, 0, At, B0); PG8_MMA(1, 1, At, B1); PG8_BAR; PG8_SCHED;
	s_add_i32 s4, s4, s24
	v_lshl_add_u64 v[236:237], v[236:237], 0, s[28:29]
	s_mov_b32 m0, s4
	ds_read_b128 v[184:187], v188 offset:49152
	ds_read_b128 v[190:193], v188 offset:50176
	ds_read_b128 v[212:215], v188 offset:51200
	ds_read_b128 v[216:219], v188 offset:52224
	ds_read_b128 v[220:223], v188 offset:53248
	ds_read_b128 v[224:227], v188 offset:54272
	ds_read_b128 v[228:231], v188 offset:55296
	ds_read_b128 v[232:235], v188 offset:56320
	global_load_lds_dwordx4 v[236:237], off
	s_add_i32 m0, s4, 0x2000
	s_add_u32 s22, s52, 0x160080
	v_lshl_add_u64 v[236:237], v[238:239], 0, s[28:29]
	s_addc_u32 s23, s53, 0
	s_add_i32 s4, s5, s24
	global_load_lds_dwordx4 v[236:237], off
	v_lshl_add_u64 v[236:237], s[22:23], 0, v[4:5]
	s_mov_b32 m0, s4
	s_nop 0
	global_load_lds_dwordx4 v[236:237], off
	v_lshl_add_u64 v[236:237], s[22:23], 0, v[170:171]
	s_add_i32 m0, s4, 0x2000
	s_nop 0
	global_load_lds_dwordx4 v[236:237], off
	v_lshl_add_u64 v[236:237], v[240:241], 0, s[28:29]
	s_mov_b32 m0, s61
	s_nop 0
	global_load_lds_dwordx4 v[236:237], off
	v_lshl_add_u64 v[236:237], v[242:243], 0, s[28:29]
	s_mov_b32 m0, s64
	s_nop 0
	global_load_lds_dwordx4 v[236:237], off
	s_waitcnt vmcnt(8)
	s_waitcnt lgkmcnt(0)
	s_barrier
	v_mfma_f32_16x16x32_bf16 v[58:61], v[134:137], v[184:187], v[58:61]
	v_mfma_f32_16x16x32_bf16 v[58:61], v[138:141], v[190:193], v[58:61]
	v_mfma_f32_16x16x32_bf16 v[54:57], v[142:145], v[184:187], v[54:57]
	v_mfma_f32_16x16x32_bf16 v[54:57], v[146:149], v[190:193], v[54:57]
	v_mfma_f32_16x16x32_bf16 v[50:53], v[134:137], v[212:215], v[50:53]
	v_mfma_f32_16x16x32_bf16 v[50:53], v[138:141], v[216:219], v[50:53]
	v_mfma_f32_16x16x32_bf16 v[46:49], v[142:145], v[212:215], v[46:49]
	v_mfma_f32_16x16x32_bf16 v[46:49], v[146:149], v[216:219], v[46:49]
	v_mfma_f32_16x16x32_bf16 v[34:37], v[134:137], v[220:223], v[34:37]
	v_mfma_f32_16x16x32_bf16 v[34:37], v[138:141], v[224:227], v[34:37]
	v_mfma_f32_16x16x32_bf16 v[30:33], v[142:145], v[220:223], v[30:33]
	v_mfma_f32_16x16x32_bf16 v[30:33], v[146:149], v[224:227], v[30:33]
	v_mfma_f32_16x16x32_bf16 v[18:21], v[134:137], v[228:231], v[18:21]
	v_mfma_f32_16x16x32_bf16 v[18:21], v[138:141], v[232:235], v[18:21]
	v_mfma_f32_16x16x32_bf16 v[14:17], v[142:145], v[228:231], v[14:17]
	v_mfma_f32_16x16x32_bf16 v[14:17], v[146:149], v[232:235], v[14:17]
	v_mfma_f32_16x16x32_bf16 v[66:69], v[150:153], v[184:187], v[66:69]
	v_mfma_f32_16x16x32_bf16 v[66:69], v[154:157], v[190:193], v[66:69]
	v_mfma_f32_16x16x32_bf16 v[62:65], v[176:179], v[184:187], v[62:65]
	v_mfma_f32_16x16x32_bf16 v[62:65], v[180:183], v[190:193], v[62:65]
	v_mfma_f32_16x16x32_bf16 v[42:45], v[150:153], v[212:215], v[42:45]
	v_mfma_f32_16x16x32_bf16 v[42:45], v[154:157], v[216:219], v[42:45]
	v_mfma_f32_16x16x32_bf16 v[38:41], v[176:179], v[212:215], v[38:41]
	v_mfma_f32_16x16x32_bf16 v[38:41], v[180:183], v[216:219], v[38:41]
	v_mfma_f32_16x16x32_bf16 v[26:29], v[150:153], v[220:223], v[26:29]
	v_mfma_f32_16x16x32_bf16 v[26:29], v[154:157], v[224:227], v[26:29]
	v_mfma_f32_16x16x32_bf16 v[22:25], v[176:179], v[220:223], v[22:25]
	v_mfma_f32_16x16x32_bf16 v[22:25], v[180:183], v[224:227], v[22:25]
	v_mfma_f32_16x16x32_bf16 v[10:13], v[150:153], v[228:231], v[10:13]
	v_mfma_f32_16x16x32_bf16 v[10:13], v[154:157], v[232:235], v[10:13]
	v_mfma_f32_16x16x32_bf16 v[6:9], v[176:179], v[228:231], v[6:9]
	v_mfma_f32_16x16x32_bf16 v[6:9], v[180:183], v[232:235], v[6:9]
	s_barrier
	s_add_i32 s20, s20, 2
	s_add_u32 s33, s33, 0x100
	s_addc_u32 s69, s69, 0
	s_cmpk_gt_u32 s20, 0x55
	s_mov_b64 s[22:23], s[50:51]
	s_cbranch_scc0 .LBB0_299
	s_and_b64 vcc, exec, s[46:47]
	s_cbranch_vccz .LBB0_302
	s_barrier

; #define PG8_STAGE(bufoff, gbase, voff) do { _Pragma("unroll") for (int _i = 0; _i < 2; ++_i) \
;         __builtin_amdgcn_global_load_lds((const unsigned*)((const char*)(gbase) + (voff)[_i]), (PG8_LAS unsigned*)(lds + (bufoff) + ldsw + _i * 8192), 16, 0, 0); } while (0)
; #define PG8_LDA(dst, b, h) do { _Pragma("unroll") for (int m = 0; m < 4; ++m) _Pragma("unroll") for (int k = 0; k < 2; ++k) dst[m][k] = *(const PG8_LAS bf16x8*)(lds + PG8_SA(b, h) + aoff + m * 2048 + k * 1024); } while (0)
; #define PG8_LDB(dst, b, h) do { _Pragma("unroll") for (int n = 0; n < 2; ++n) _Pragma("unroll") for (int k = 0; k < 2; ++k) dst[n][k] = *(const PG8_LAS bf16x8*)(lds + PG8_SB(b, h) + boff + n * 2048 + k * 1024); } while (0)
; #define PG8_MMA(ai, bj, At, Bt) do { __builtin_amdgcn_s_setprio(1); _Pragma("unroll") for (int m = 0; m < 4; ++m) _Pragma("unroll") for (int n = 0; n < 2; ++n) _Pragma("unroll") for (int k = 0; k < 2; ++k) \
;         acc[ai][bj][m][n] = __builtin_amdgcn_mfma_f32_16x16x32_bf16(Bt[n][k], At[m][k], acc[ai][bj][m][n], 0, 0, 0); __builtin_amdgcn_s_setprio(0); } while (0)
; #define PG8_WAIT_V(n) asm volatile("s_waitcnt vmcnt(" #n ")" ::: "memory")
; #define PG8_WAIT_L(n) asm volatile("s_waitcnt lgkmcnt(" #n ")" ::: "memory")
; #define PG8_BAR __builtin_amdgcn_s_barrier()
; #define PG8_SCHED __builtin_amdgcn_sched_barrier(0)
; template <class Epi, class Sched, bool ALIGN_EPI = false, bool SP2 = false>
; __device__ __forceinline__ void gemm_phase(PG8_LAS unsigned char* lds, const Gemm g, const Sched& S, const Epi& E) {
;     ...
;             const bool last = (t == nt - 2);
;             const char* a1 = cA + (size_t)(t + 1) * kstep;
;             const char* a2 = last ? nA : cA + (size_t)(t + 2) * kstep; const char* b2 = last ? nB : cB + (size_t)(t + 2) * kstep;
;             const char* a3 = a2 + kstep; const char* b3 = b2 + kstep;
;             if (last && has_next) S.a_ready(nxt);
;             if constexpr (SP2) {
;             PG8_LDB(B0, 0, 0); PG8_LDB(B1, 0, 1); PG8_SCHED; PG8_LDA(At, 0, 0); PG8_STAGE(PG8_SA(1, 1), a1 + hstep, voffA);
;             PG8_WAIT_V(8); PG8_WAIT_L(0); PG8_BAR; PG8_MMA(0, 0, At, B0); PG8_MMA(0, 1, At, B1); PG8_BAR; PG8_SCHED;
;             PG8_LDA(At, 0, 1); PG8_STAGE(PG8_SB(0, 0), b2, voffB); PG8_STAGE(PG8_SB(0, 1), b2 + hstep, voffB); PG8_STAGE(PG8_SA(0, 0), a2, voffA);
.LBB0_387:
	s_add_u32 s4, s56, 0xfff80080
	s_addc_u32 s5, s57, -1
	s_add_i32 s6, 0, 0x10000
	s_cmp_eq_u32 s20, 28
	s_cselect_b32 s59, s47, s5
	s_cselect_b32 s58, s75, s4
	v_add_u32_e32 v156, s6, v153
	s_cselect_b32 s55, s49, s77
	s_cselect_b32 s54, vcc_lo, s71
	s_add_i32 s4, 0, 0x14000
	ds_read_b128 v[144:147], v156
	ds_read_b128 v[148:151], v156 offset:1024
	ds_read_b128 v[168:171], v156 offset:2048
	ds_read_b128 v[172:175], v156 offset:3072
	v_add_u32_e32 v156, s4, v153
	ds_read_b128 v[176:179], v156
	ds_read_b128 v[180:183], v156 offset:1024
	ds_read_b128 v[184:187], v156 offset:2048
	ds_read_b128 v[188:191], v156 offset:3072
	v_lshl_add_u64 v[156:157], s[56:57], 0, v[140:141]
	s_add_i32 m0, s60, 0xc000
	ds_read_b128 v[212:215], v155
	ds_read_b128 v[216:219], v155 offset:1024
	ds_read_b128 v[220:223], v155 offset:2048
	ds_read_b128 v[224:227], v155 offset:3072
	ds_read_b128 v[228:231], v155 offset:4096
	ds_read_b128 v[232:235], v155 offset:5120
	ds_read_b128 v[236:239], v155 offset:6144
	ds_read_b128 v[240:243], v155 offset:7168
	global_load_lds_dwordx4 v[156:157], off
	v_lshl_add_u64 v[156:157], s[56:57], 0, v[142:143]
	s_add_i32 m0, s60, 0xe000
	s_nop 0
	global_load_lds_dwordx4 v[156:157], off
	s_waitcnt vmcnt(8)
	s_waitcnt lgkmcnt(0)
	s_barrier
	v_mfma_f32_16x16x32_bf16 v[122:125], v[144:147], v[212:215], v[122:125]
	v_mfma_f32_16x16x32_bf16 v[122:125], v[148:151], v[216:219], v[122:125]
	v_mfma_f32_16x16x32_bf16 v[118:121], v[168:171], v[212:215], v[118:121]
	v_mfma_f32_16x16x32_bf16 v[118:121], v[172:175], v[216:219], v[118:121]
	v_mfma_f32_16x16x32_bf16 v[106:109], v[144:147], v[220:223], v[106:109]
	v_mfma_f32_16x16x32_bf16 v[106:109], v[148:151], v[224:227], v[106:109]
	v_mfma_f32_16x16x32_bf16 v[102:105], v[168:171], v[220:223], v[102:105]
	v_mfma_f32_16x16x32_bf16 v[102:105], v[172:175], v[224:227], v[102:105]
	v_mfma_f32_16x16x32_bf16 v[90:93], v[144:147], v[228:231], v[90:93]
	v_mfma_f32_16x16x32_bf16 v[90:93], v[148:151], v[232:235], v[90:93]
	v_mfma_f32_16x16x32_bf16 v[86:89], v[168:171], v[228:231], v[86:89]
	v_mfma_f32_16x16x32_bf16 v[86:89], v[172:175], v[232:235], v[86:89]
	v_mfma_f32_16x16x32_bf16 v[74:77], v[144:147], v[236:239], v[74:77]
	v_mfma_f32_16x16x32_bf16 v[74:77], v[148:151], v[240:243], v[74:77]
	v_mfma_f32_16x16x32_bf16 v[70:73], v[168:171], v[236:239], v[70:73]
	v_mfma_f32_16x16x32_bf16 v[70:73], v[172:175], v[240:243], v[70:73]
	v_mfma_f32_16x16x32_bf16 v[130:133], v[176:179], v[212:215], v[130:133]
	v_mfma_f32_16x16x32_bf16 v[130:133], v[180:183], v[216:219], v[130:133]
	v_mfma_f32_16x16x32_bf16 v[126:129], v[184:187], v[212:215], v[126:129]
	v_mfma_f32_16x16x32_bf16 v[126:129], v[188:191], v[216:219], v[126:129]
	v_mfma_f32_16x16x32_bf16 v[114:117], v[176:179], v[220:223], v[114:117]
	v_mfma_f32_16x16x32_bf16 v[114:117], v[180:183], v[224:227], v[114:117]
	v_mfma_f32_16x16x32_bf16 v[110:113], v[184:187], v[220:223], v[110:113]
	v_mfma_f32_16x16x32_bf16 v[110:113], v[188:191], v[224:227], v[110:113]
	v_mfma_f32_16x16x32_bf16 v[98:101], v[176:179], v[228:231], v[98:101]
	v_mfma_f32_16x16x32_bf16 v[98:101], v[180:183], v[232:235], v[98:101]
	v_mfma_f32_16x16x32_bf16 v[94:97], v[184:187], v[228:231], v[94:97]
	v_mfma_f32_16x16x32_bf16 v[94:97], v[188:191], v[232:235], v[94:97]
	v_mfma_f32_16x16x32_bf16 v[82:85], v[176:179], v[236:239], v[82:85]
	v_mfma_f32_16x16x32_bf16 v[82:85], v[180:183], v[240:243], v[82:85]
	v_mfma_f32_16x16x32_bf16 v[78:81], v[184:187], v[236:239], v[78:81]
	v_mfma_f32_16x16x32_bf16 v[78:81], v[188:191], v[240:243], v[78:81]
	s_barrier
	s_add_i32 s5, s6, s24
	v_lshl_add_u64 v[156:157], s[54:55], 0, v[4:5]
	s_mov_b32 m0, s5
	ds_read_b128 v[212:215], v155 offset:16384
	ds_read_b128 v[216:219], v155 offset:17408
	ds_read_b128 v[220:223], v155 offset:18432
	ds_read_b128 v[224:227], v155 offset:19456
	ds_read_b128 v[228:231], v155 offset:20480
	ds_read_b128 v[232:235], v155 offset:21504
	ds_read_b128 v[236:239], v155 offset:22528
	ds_read_b128 v[240:243], v155 offset:23552
	global_load_lds_dwordx4 v[156:157], off
	s_add_i32 m0, s5, 0x2000
	s_add_u32 s34, s54, 0x80000
	v_lshl_add_u64 v[192:193], s[54:55], 0, v[2:3]
	s_addc_u32 s35, s55, 0
	s_add_i32 s4, s4, s24
	global_load_lds_dwordx4 v[192:193], off
	v_lshl_add_u64 v[244:245], s[34:35], 0, v[4:5]
	s_mov_b32 m0, s4
	v_lshl_add_u64 v[246:247], s[58:59], 0, v[134:135]
	global_load_lds_dwordx4 v[244:245], off
	v_lshl_add_u64 v[244:245], s[34:35], 0, v[2:3]
	s_add_i32 m0, s4, 0x2000
	s_nop 0
	global_load_lds_dwordx4 v[244:245], off
	v_lshl_add_u64 v[244:245], s[58:59], 0, v[136:137]
	s_mov_b32 m0, s60
	s_nop 0
	global_load_lds_dwordx4 v[244:245], off
	s_mov_b32 m0, s61
	s_nop 0
	global_load_lds_dwordx4 v[246:247], off
	s_waitcnt vmcnt(8)
	s_waitcnt lgkmcnt(0)
	s_barrier
; #define PG8_STAGE(bufoff, gbase, voff) do { _Pragma("unroll") for (int _i = 0; _i < 2; ++_i) \
;         __builtin_amdgcn_global_load_lds((const unsigned*)((const char*)(gbase) + (voff)[_i]), (PG8_LAS unsigned*)(lds + (bufoff) + ldsw + _i * 8192), 16, 0, 0); } while (0)
; #define PG8_LDA(dst, b, h) do { _Pragma("unroll") for (int m = 0; m < 4; ++m) _Pragma("unroll") for (int k = 0; k < 2; ++k) dst[m][k] = *(const PG8_LAS bf16x8*)(lds + PG8_SA(b, h) + aoff + m * 2048 + k * 1024); } while (0)
; #define PG8_LDB(dst, b, h) do { _Pragma("unroll") for (int n = 0; n < 2; ++n) _Pragma("unroll") for (int k = 0; k < 2; ++k) dst[n][k] = *(const PG8_LAS bf16x8*)(lds + PG8_SB(b, h) + boff + n * 2048 + k * 1024); } while (0)
; #define PG8_MMA(ai, bj, At, Bt) do { __builtin_amdgcn_s_setprio(1); _Pragma("unroll") for (int m = 0; m < 4; ++m) _Pragma("unroll") for (int n = 0; n < 2; ++n) _Pragma("unroll") for (int k = 0; k < 2; ++k) \
;         acc[ai][bj][m][n] = __builtin_amdgcn_mfma_f32_16x16x32_bf16(Bt[n][k], At[m][k], acc[ai][bj][m][n], 0, 0, 0); __builtin_amdgcn_s_setprio(0); } while (0)
; #define PG8_WAIT_V(n) asm volatile("s_waitcnt vmcnt(" #n ")" ::: "memory")
; #define PG8_WAIT_L(n) asm volatile("s_waitcnt lgkmcnt(" #n ")" ::: "memory")
; #define PG8_BAR __builtin_amdgcn_s_barrier()
; #define PG8_SCHED __builtin_amdgcn_sched_barrier(0)
; template <class Epi, class Sched, bool ALIGN_EPI = false, bool SP2 = false>
; __device__ __forceinline__ void gemm_phase(PG8_LAS unsigned char* lds, const Gemm g, const Sched& S, const Epi& E) {
;     ...
;             PG8_WAIT_V(8); PG8_WAIT_L(0); PG8_BAR; PG8_MMA(1, 0, At, B0); PG8_MMA(1, 1, At, B1); PG8_BAR; PG8_SCHED;
;             PG8_LDB(B0, 1, 0); PG8_LDB(B1, 1, 1); PG8_SCHED; PG8_LDA(At, 1, 0); PG8_STAGE(PG8_SA(0, 1), a2 + hstep, voffA);
;             PG8_WAIT_V(8); PG8_WAIT_L(0); PG8_BAR; PG8_MMA(0, 0, At, B0); PG8_MMA(0, 1, At, B1); PG8_BAR; PG8_SCHED;
	v_mfma_f32_16x16x32_bf16 v[58:61], v[144:147], v[212:215], v[58:61]
	v_mfma_f32_16x16x32_bf16 v[58:61], v[148:151], v[216:219], v[58:61]
	v_mfma_f32_16x16x32_bf16 v[54:57], v[168:171], v[212:215], v[54:57]
	v_mfma_f32_16x16x32_bf16 v[54:57], v[172:175], v[216:219], v[54:57]
	v_mfma_f32_16x16x32_bf16 v[42:45], v[144:147], v[220:223], v[42:45]
	v_mfma_f32_16x16x32_bf16 v[42:45], v[148:151], v[224:227], v[42:45]
	v_mfma_f32_16x16x32_bf16 v[38:41], v[168:171], v[220:223], v[38:41]
	v_mfma_f32_16x16x32_bf16 v[38:41], v[172:175], v[224:227], v[38:41]
	v_mfma_f32_16x16x32_bf16 v[26:29], v[144:147], v[228:231], v[26:29]
	v_mfma_f32_16x16x32_bf16 v[26:29], v[148:151], v[232:235], v[26:29]
	v_mfma_f32_16x16x32_bf16 v[22:25], v[168:171], v[228:231], v[22:25]
	v_mfma_f32_16x16x32_bf16 v[22:25], v[172:175], v[232:235], v[22:25]
	v_mfma_f32_16x16x32_bf16 v[10:13], v[144:147], v[236:239], v[10:13]
	v_mfma_f32_16x16x32_bf16 v[10:13], v[148:151], v[240:243], v[10:13]
	v_mfma_f32_16x16x32_bf16 v[6:9], v[168:171], v[236:239], v[6:9]
	v_mfma_f32_16x16x32_bf16 v[6:9], v[172:175], v[240:243], v[6:9]
	v_mfma_f32_16x16x32_bf16 v[66:69], v[176:179], v[212:215], v[66:69]
	v_mfma_f32_16x16x32_bf16 v[66:69], v[180:183], v[216:219], v[66:69]
	v_mfma_f32_16x16x32_bf16 v[62:65], v[184:187], v[212:215], v[62:65]
	v_mfma_f32_16x16x32_bf16 v[62:65], v[188:191], v[216:219], v[62:65]
	v_mfma_f32_16x16x32_bf16 v[50:53], v[176:179], v[220:223], v[50:53]
	v_mfma_f32_16x16x32_bf16 v[50:53], v[180:183], v[224:227], v[50:53]
	v_mfma_f32_16x16x32_bf16 v[46:49], v[184:187], v[220:223], v[46:49]
	v_mfma_f32_16x16x32_bf16 v[46:49], v[188:191], v[224:227], v[46:49]
	v_mfma_f32_16x16x32_bf16 v[34:37], v[176:179], v[228:231], v[34:37]
	v_mfma_f32_16x16x32_bf16 v[34:37], v[180:183], v[232:235], v[34:37]
	v_mfma_f32_16x16x32_bf16 v[30:33], v[184:187], v[228:231], v[30:33]
	v_mfma_f32_16x16x32_bf16 v[30:33], v[188:191], v[232:235], v[30:33]
	v_mfma_f32_16x16x32_bf16 v[14:17], v[176:179], v[236:239], v[14:17]
	v_mfma_f32_16x16x32_bf16 v[14:17], v[180:183], v[240:243], v[14:17]
	v_mfma_f32_16x16x32_bf16 v[18:21], v[184:187], v[236:239], v[18:21]
	v_mfma_f32_16x16x32_bf16 v[18:21], v[188:191], v[240:243], v[18:21]
	s_barrier
	s_add_i32 s4, 0, 0x18000
	v_add_u32_e32 v158, s4, v153
	s_add_i32 s5, 0, 0x1c000
	ds_read_b128 v[144:147], v158
	ds_read_b128 v[148:151], v158 offset:1024
	ds_read_b128 v[168:171], v158 offset:2048
	ds_read_b128 v[172:175], v158 offset:3072
	v_add_u32_e32 v158, s5, v153
	ds_read_b128 v[176:179], v158
	ds_read_b128 v[180:183], v158 offset:1024
	ds_read_b128 v[184:187], v158 offset:2048
	ds_read_b128 v[188:191], v158 offset:3072
	s_add_u32 s34, s58, 0x80000
	s_addc_u32 s35, s59, 0
	s_mov_b32 m0, s64
	v_lshl_add_u64 v[248:249], s[34:35], 0, v[136:137]
	ds_read_b128 v[212:215], v155 offset:32768
	ds_read_b128 v[216:219], v155 offset:33792
	ds_read_b128 v[220:223], v155 offset:34816
	ds_read_b128 v[224:227], v155 offset:35840
	ds_read_b128 v[228:231], v155 offset:36864
	ds_read_b128 v[232:235], v155 offset:37888
	ds_read_b128 v[236:239], v155 offset:38912
	ds_read_b128 v[240:243], v155 offset:39936
	global_load_lds_dwordx4 v[248:249], off
	v_lshl_add_u64 v[248:249], s[34:35], 0, v[134:135]
	s_mov_b32 m0, s65
	s_nop 0
	global_load_lds_dwordx4 v[248:249], off
	s_waitcnt vmcnt(8)
	s_waitcnt lgkmcnt(0)
	s_barrier
	v_mfma_f32_16x16x32_bf16 v[122:125], v[144:147], v[212:215], v[122:125]
	v_mfma_f32_16x16x32_bf16 v[122:125], v[148:151], v[216:219], v[122:125]
	v_mfma_f32_16x16x32_bf16 v[118:121], v[168:171], v[212:215], v[118:121]
	v_mfma_f32_16x16x32_bf16 v[118:121], v[172:175], v[216:219], v[118:121]
	v_mfma_f32_16x16x32_bf16 v[106:109], v[144:147], v[220:223], v[106:109]
	v_mfma_f32_16x16x32_bf16 v[106:109], v[148:151], v[224:227], v[106:109]
	v_mfma_f32_16x16x32_bf16 v[102:105], v[168:171], v[220:223], v[102:105]
	v_mfma_f32_16x16x32_bf16 v[102:105], v[172:175], v[224:227], v[102:105]
	v_mfma_f32_16x16x32_bf16 v[90:93], v[144:147], v[228:231], v[90:93]
	v_mfma_f32_16x16x32_bf16 v[90:93], v[148:151], v[232:235], v[90:93]
	v_mfma_f32_16x16x32_bf16 v[86:89], v[168:171], v[228:231], v[86:89]
	v_mfma_f32_16x16x32_bf16 v[86:89], v[172:175], v[232:235], v[86:89]
	v_mfma_f32_16x16x32_bf16 v[74:77], v[144:147], v[236:239], v[74:77]
	v_mfma_f32_16x16x32_bf16 v[74:77], v[148:151], v[240:243], v[74:77]
	v_mfma_f32_16x16x32_bf16 v[70:73], v[168:171], v[236:239], v[70:73]
	v_mfma_f32_16x16x32_bf16 v[70:73], v[172:175], v[240:243], v[70:73]
	v_mfma_f32_16x16x32_bf16 v[130:133], v[176:179], v[212:215], v[130:133]
	v_mfma_f32_16x16x32_bf16 v[130:133], v[180:183], v[216:219], v[130:133]
	v_mfma_f32_16x16x32_bf16 v[126:129], v[184:187], v[212:215], v[126:129]
	v_mfma_f32_16x16x32_bf16 v[126:129], v[188:191], v[216:219], v[126:129]
	v_mfma_f32_16x16x32_bf16 v[114:117], v[176:179], v[220:223], v[114:117]
	v_mfma_f32_16x16x32_bf16 v[114:117], v[180:183], v[224:227], v[114:117]
	v_mfma_f32_16x16x32_bf16 v[110:113], v[184:187], v[220:223], v[110:113]
	v_mfma_f32_16x16x32_bf16 v[110:113], v[188:191], v[224:227], v[110:113]
	v_mfma_f32_16x16x32_bf16 v[98:101], v[176:179], v[228:231], v[98:101]
	v_mfma_f32_16x16x32_bf16 v[98:101], v[180:183], v[232:235], v[98:101]
	v_mfma_f32_16x16x32_bf16 v[94:97], v[184:187], v[228:231], v[94:97]
	v_mfma_f32_16x16x32_bf16 v[94:97], v[188:191], v[232:235], v[94:97]
	v_mfma_f32_16x16x32_bf16 v[82:85], v[176:179], v[236:239], v[82:85]
	v_mfma_f32_16x16x32_bf16 v[82:85], v[180:183], v[240:243], v[82:85]
	v_mfma_f32_16x16x32_bf16 v[78:81], v[184:187], v[236:239], v[78:81]
	v_mfma_f32_16x16x32_bf16 v[78:81], v[188:191], v[240:243], v[78:81]
	s_barrier
; #define PG8_STAGE(bufoff, gbase, voff) do { _Pragma("unroll") for (int _i = 0; _i < 2; ++_i) \
;         __builtin_amdgcn_global_load_lds((const unsigned*)((const char*)(gbase) + (voff)[_i]), (PG8_LAS unsigned*)(lds + (bufoff) + ldsw + _i * 8192), 16, 0, 0); } while (0)
; #define PG8_LDA(dst, b, h) do { _Pragma("unroll") for (int m = 0; m < 4; ++m) _Pragma("unroll") for (int k = 0; k < 2; ++k) dst[m][k] = *(const PG8_LAS bf16x8*)(lds + PG8_SA(b, h) + aoff + m * 2048 + k * 1024); } while (0)
; #define PG8_MMA(ai, bj, At, Bt) do { __builtin_amdgcn_s_setprio(1); _Pragma("unroll") for (int m = 0; m < 4; ++m) _Pragma("unroll") for (int n = 0; n < 2; ++n) _Pragma("unroll") for (int k = 0; k < 2; ++k) \
;         acc[ai][bj][m][n] = __builtin_amdgcn_mfma_f32_16x16x32_bf16(Bt[n][k], At[m][k], acc[ai][bj][m][n], 0, 0, 0); __builtin_amdgcn_s_setprio(0); } while (0)
; #define PG8_WAIT_V(n) asm volatile("s_waitcnt vmcnt(" #n ")" ::: "memory")
; #define PG8_WAIT_L(n) asm volatile("s_waitcnt lgkmcnt(" #n ")" ::: "memory")
; #define PG8_BAR __builtin_amdgcn_s_barrier()
; #define PG8_SCHED __builtin_amdgcn_sched_barrier(0)
; template <class Epi, class Sched, bool ALIGN_EPI = false, bool SP2 = false>
; __device__ __forceinline__ void gemm_phase(PG8_LAS unsigned char* lds, const Gemm g, const Sched& S, const Epi& E) {
;     ...
;         for (int t = 0; t < nt; t += 2) {
;     ...
;             PG8_LDA(At, 1, 1); PG8_STAGE(PG8_SB(1, 0), b3, voffB); PG8_STAGE(PG8_SB(1, 1), b3 + hstep, voffB); PG8_STAGE(PG8_SA(1, 0), a3, voffA);
;             PG8_WAIT_V(8); PG8_WAIT_L(0); PG8_BAR; PG8_MMA(1, 0, At, B0); PG8_MMA(1, 1, At, B1); PG8_BAR; PG8_SCHED;
	s_add_i32 s4, s4, s24
	v_lshl_add_u64 v[156:157], v[156:157], 0, s[28:29]
	s_mov_b32 m0, s4
	ds_read_b128 v[212:215], v155 offset:49152
	ds_read_b128 v[216:219], v155 offset:50176
	ds_read_b128 v[220:223], v155 offset:51200
	ds_read_b128 v[224:227], v155 offset:52224
	ds_read_b128 v[228:231], v155 offset:53248
	ds_read_b128 v[232:235], v155 offset:54272
	ds_read_b128 v[236:239], v155 offset:55296
	ds_read_b128 v[240:243], v155 offset:56320
	global_load_lds_dwordx4 v[156:157], off
	s_add_i32 m0, s4, 0x2000
	s_add_u32 s34, s54, 0x80080
	v_lshl_add_u64 v[156:157], v[192:193], 0, s[28:29]
	s_addc_u32 s35, s55, 0
	s_add_i32 s4, s5, s24
	global_load_lds_dwordx4 v[156:157], off
	v_lshl_add_u64 v[156:157], s[34:35], 0, v[4:5]
	s_mov_b32 m0, s4
	s_nop 0
	global_load_lds_dwordx4 v[156:157], off
	v_lshl_add_u64 v[156:157], s[34:35], 0, v[2:3]
	s_add_i32 m0, s4, 0x2000
	s_nop 0
	global_load_lds_dwordx4 v[156:157], off
	v_lshl_add_u64 v[156:157], v[244:245], 0, s[28:29]
	s_mov_b32 m0, s67
	s_nop 0
	global_load_lds_dwordx4 v[156:157], off
	v_lshl_add_u64 v[156:157], v[246:247], 0, s[28:29]
	s_mov_b32 m0, s72
	s_nop 0
	global_load_lds_dwordx4 v[156:157], off
	s_waitcnt vmcnt(8)
	s_waitcnt lgkmcnt(0)
	s_barrier
	v_mfma_f32_16x16x32_bf16 v[58:61], v[144:147], v[212:215], v[58:61]
	v_mfma_f32_16x16x32_bf16 v[58:61], v[148:151], v[216:219], v[58:61]
	v_mfma_f32_16x16x32_bf16 v[54:57], v[168:171], v[212:215], v[54:57]
	v_mfma_f32_16x16x32_bf16 v[54:57], v[172:175], v[216:219], v[54:57]
	v_mfma_f32_16x16x32_bf16 v[42:45], v[144:147], v[220:223], v[42:45]
	v_mfma_f32_16x16x32_bf16 v[42:45], v[148:151], v[224:227], v[42:45]
	v_mfma_f32_16x16x32_bf16 v[38:41], v[168:171], v[220:223], v[38:41]
	v_mfma_f32_16x16x32_bf16 v[38:41], v[172:175], v[224:227], v[38:41]
	v_mfma_f32_16x16x32_bf16 v[26:29], v[144:147], v[228:231], v[26:29]
	v_mfma_f32_16x16x32_bf16 v[26:29], v[148:151], v[232:235], v[26:29]
	v_mfma_f32_16x16x32_bf16 v[22:25], v[168:171], v[228:231], v[22:25]
	v_mfma_f32_16x16x32_bf16 v[22:25], v[172:175], v[232:235], v[22:25]
	v_mfma_f32_16x16x32_bf16 v[10:13], v[144:147], v[236:239], v[10:13]
	v_mfma_f32_16x16x32_bf16 v[10:13], v[148:151], v[240:243], v[10:13]
	v_mfma_f32_16x16x32_bf16 v[6:9], v[168:171], v[236:239], v[6:9]
	v_mfma_f32_16x16x32_bf16 v[6:9], v[172:175], v[240:243], v[6:9]
	v_mfma_f32_16x16x32_bf16 v[66:69], v[176:179], v[212:215], v[66:69]
	v_mfma_f32_16x16x32_bf16 v[66:69], v[180:183], v[216:219], v[66:69]
	v_mfma_f32_16x16x32_bf16 v[62:65], v[184:187], v[212:215], v[62:65]
	v_mfma_f32_16x16x32_bf16 v[62:65], v[188:191], v[216:219], v[62:65]
	v_mfma_f32_16x16x32_bf16 v[50:53], v[176:179], v[220:223], v[50:53]
	v_mfma_f32_16x16x32_bf16 v[50:53], v[180:183], v[224:227], v[50:53]
	v_mfma_f32_16x16x32_bf16 v[46:49], v[184:187], v[220:223], v[46:49]
	v_mfma_f32_16x16x32_bf16 v[46:49], v[188:191], v[224:227], v[46:49]
	v_mfma_f32_16x16x32_bf16 v[34:37], v[176:179], v[228:231], v[34:37]
	v_mfma_f32_16x16x32_bf16 v[34:37], v[180:183], v[232:235], v[34:37]
	v_mfma_f32_16x16x32_bf16 v[30:33], v[184:187], v[228:231], v[30:33]
	v_mfma_f32_16x16x32_bf16 v[30:33], v[188:191], v[232:235], v[30:33]
	v_mfma_f32_16x16x32_bf16 v[14:17], v[176:179], v[236:239], v[14:17]
	v_mfma_f32_16x16x32_bf16 v[14:17], v[180:183], v[240:243], v[14:17]
	v_mfma_f32_16x16x32_bf16 v[18:21], v[184:187], v[236:239], v[18:21]
	v_mfma_f32_16x16x32_bf16 v[18:21], v[188:191], v[240:243], v[18:21]
	s_barrier
	s_add_i32 s20, s20, 2
	s_add_u32 s56, s56, 0x100
	s_addc_u32 s57, s57, 0
	s_add_u32 s71, s71, 0x100
	s_addc_u32 s77, s77, 0
	s_cmp_gt_u32 s20, 29
	s_cbranch_scc0 .LBB0_387
	s_and_b64 vcc, exec, s[44:45]
	s_movk_i32 s75, 0x800
	s_movk_i32 s77, 0x6000
	s_mov_b32 s71, 0x44800000
	s_cbranch_vccz .LBB0_390
	s_barrier

; #define PG8_STAGE(bufoff, gbase, voff) do { _Pragma("unroll") for (int _i = 0; _i < 2; ++_i) \
;         __builtin_amdgcn_global_load_lds((const unsigned*)((const char*)(gbase) + (voff)[_i]), (PG8_LAS unsigned*)(lds + (bufoff) + ldsw + _i * 8192), 16, 0, 0); } while (0)
; #define PG8_LDA(dst, b, h) do { _Pragma("unroll") for (int m = 0; m < 4; ++m) _Pragma("unroll") for (int k = 0; k < 2; ++k) dst[m][k] = *(const PG8_LAS bf16x8*)(lds + PG8_SA(b, h) + aoff + m * 2048 + k * 1024); } while (0)
; #define PG8_LDB(dst, b, h) do { _Pragma("unroll") for (int n = 0; n < 2; ++n) _Pragma("unroll") for (int k = 0; k < 2; ++k) dst[n][k] = *(const PG8_LAS bf16x8*)(lds + PG8_SB(b, h) + boff + n * 2048 + k * 1024); } while (0)
; #define PG8_MMA(ai, bj, At, Bt) do { __builtin_amdgcn_s_setprio(1); _Pragma("unroll") for (int m = 0; m < 4; ++m) _Pragma("unroll") for (int n = 0; n < 2; ++n) _Pragma("unroll") for (int k = 0; k < 2; ++k) \
;         acc[ai][bj][m][n] = __builtin_amdgcn_mfma_f32_16x16x32_bf16(Bt[n][k], At[m][k], acc[ai][bj][m][n], 0, 0, 0); __builtin_amdgcn_s_setprio(0); } while (0)
; #define PG8_WAIT_V(n) asm volatile("s_waitcnt vmcnt(" #n ")" ::: "memory")
; #define PG8_WAIT_L(n) asm volatile("s_waitcnt lgkmcnt(" #n ")" ::: "memory")
; #define PG8_BAR __builtin_amdgcn_s_barrier()
; #define PG8_SCHED __builtin_amdgcn_sched_barrier(0)
; template <class Epi, class Sched, bool ALIGN_EPI = false, bool SP2 = false>
; __device__ __forceinline__ void gemm_phase(PG8_LAS unsigned char* lds, const Gemm g, const Sched& S, const Epi& E) {
;     ...
;             const bool last = (t == nt - 2);
;             const char* a1 = cA + (size_t)(t + 1) * kstep;
;             const char* a2 = last ? nA : cA + (size_t)(t + 2) * kstep; const char* b2 = last ? nB : cB + (size_t)(t + 2) * kstep;
;             const char* a3 = a2 + kstep; const char* b3 = b2 + kstep;
;             if (last && has_next) S.a_ready(nxt);
;             if constexpr (SP2) {
;             PG8_LDB(B0, 0, 0); PG8_LDB(B1, 0, 1); PG8_SCHED; PG8_LDA(At, 0, 0); PG8_STAGE(PG8_SA(1, 1), a1 + hstep, voffA);
;             PG8_WAIT_V(8); PG8_WAIT_L(0); PG8_BAR; PG8_MMA(0, 0, At, B0); PG8_MMA(0, 1, At, B1); PG8_BAR; PG8_SCHED;
;             PG8_LDA(At, 0, 1); PG8_STAGE(PG8_SB(0, 0), b2, voffB); PG8_STAGE(PG8_SB(0, 1), b2 + hstep, voffB); PG8_STAGE(PG8_SA(0, 0), a2, voffA);
.LBB0_1738:
	s_add_u32 s4, s50, 0xfff80080
	s_addc_u32 s5, s51, -1
	s_add_i32 s6, 0, 0x10000
	s_cmp_eq_u32 s20, 28
	s_cselect_b32 s53, s43, s5
	s_cselect_b32 s52, s66, s4
	s_cselect_b32 s49, s45, s71
	s_cselect_b32 s48, s67, s69
	s_add_i32 s4, 0, 0x14000
	v_add_u32_e32 v146, s6, v158
	v_add_u32_e32 v180, s4, v158
	ds_read_b128 v[134:137], v146
	ds_read_b128 v[138:141], v146 offset:1024
	ds_read_b128 v[142:145], v146 offset:2048
	ds_read_b128 v[146:149], v146 offset:3072
	ds_read_b128 v[150:153], v180
	ds_read_b128 v[154:157], v180 offset:1024
	ds_read_b128 v[176:179], v180 offset:2048
	ds_read_b128 v[180:183], v180 offset:3072
	v_lshl_add_u64 v[234:235], s[50:51], 0, v[172:173]
	s_add_i32 m0, s54, 0xc000
	ds_read_b128 v[184:187], v188
	ds_read_b128 v[190:193], v188 offset:1024
	ds_read_b128 v[210:213], v188 offset:2048
	ds_read_b128 v[214:217], v188 offset:3072
	ds_read_b128 v[218:221], v188 offset:4096
	ds_read_b128 v[222:225], v188 offset:5120
	ds_read_b128 v[226:229], v188 offset:6144
	ds_read_b128 v[230:233], v188 offset:7168
	global_load_lds_dwordx4 v[234:235], off
	v_lshl_add_u64 v[234:235], s[50:51], 0, v[174:175]
	s_add_i32 m0, s54, 0xe000
	s_nop 0
	global_load_lds_dwordx4 v[234:235], off
	s_waitcnt vmcnt(8)
	s_waitcnt lgkmcnt(0)
	s_barrier
	v_mfma_f32_16x16x32_bf16 v[122:125], v[134:137], v[184:187], v[122:125]
	v_mfma_f32_16x16x32_bf16 v[122:125], v[138:141], v[190:193], v[122:125]
	v_mfma_f32_16x16x32_bf16 v[118:121], v[142:145], v[184:187], v[118:121]
	v_mfma_f32_16x16x32_bf16 v[118:121], v[146:149], v[190:193], v[118:121]
	v_mfma_f32_16x16x32_bf16 v[114:117], v[134:137], v[210:213], v[114:117]
	v_mfma_f32_16x16x32_bf16 v[114:117], v[138:141], v[214:217], v[114:117]
	v_mfma_f32_16x16x32_bf16 v[106:109], v[142:145], v[210:213], v[106:109]
	v_mfma_f32_16x16x32_bf16 v[106:109], v[146:149], v[214:217], v[106:109]
	v_mfma_f32_16x16x32_bf16 v[98:101], v[134:137], v[218:221], v[98:101]
	v_mfma_f32_16x16x32_bf16 v[98:101], v[138:141], v[222:225], v[98:101]
	v_mfma_f32_16x16x32_bf16 v[90:93], v[142:145], v[218:221], v[90:93]
	v_mfma_f32_16x16x32_bf16 v[90:93], v[146:149], v[222:225], v[90:93]
	v_mfma_f32_16x16x32_bf16 v[82:85], v[134:137], v[226:229], v[82:85]
	v_mfma_f32_16x16x32_bf16 v[82:85], v[138:141], v[230:233], v[82:85]
	v_mfma_f32_16x16x32_bf16 v[74:77], v[142:145], v[226:229], v[74:77]
	v_mfma_f32_16x16x32_bf16 v[74:77], v[146:149], v[230:233], v[74:77]
	v_mfma_f32_16x16x32_bf16 v[130:133], v[150:153], v[184:187], v[130:133]
	v_mfma_f32_16x16x32_bf16 v[130:133], v[154:157], v[190:193], v[130:133]
	v_mfma_f32_16x16x32_bf16 v[126:129], v[176:179], v[184:187], v[126:129]
	v_mfma_f32_16x16x32_bf16 v[126:129], v[180:183], v[190:193], v[126:129]
	v_mfma_f32_16x16x32_bf16 v[110:113], v[150:153], v[210:213], v[110:113]
	v_mfma_f32_16x16x32_bf16 v[110:113], v[154:157], v[214:217], v[110:113]
	v_mfma_f32_16x16x32_bf16 v[102:105], v[176:179], v[210:213], v[102:105]
	v_mfma_f32_16x16x32_bf16 v[102:105], v[180:183], v[214:217], v[102:105]
	v_mfma_f32_16x16x32_bf16 v[94:97], v[150:153], v[218:221], v[94:97]
	v_mfma_f32_16x16x32_bf16 v[94:97], v[154:157], v[222:225], v[94:97]
	v_mfma_f32_16x16x32_bf16 v[86:89], v[176:179], v[218:221], v[86:89]
	v_mfma_f32_16x16x32_bf16 v[86:89], v[180:183], v[222:225], v[86:89]
	v_mfma_f32_16x16x32_bf16 v[78:81], v[150:153], v[226:229], v[78:81]
	v_mfma_f32_16x16x32_bf16 v[78:81], v[154:157], v[230:233], v[78:81]
	v_mfma_f32_16x16x32_bf16 v[70:73], v[176:179], v[226:229], v[70:73]
	v_mfma_f32_16x16x32_bf16 v[70:73], v[180:183], v[230:233], v[70:73]
	s_barrier
	s_add_i32 s5, s6, s24
	v_lshl_add_u64 v[234:235], s[48:49], 0, v[4:5]
	s_mov_b32 m0, s5
	ds_read_b128 v[184:187], v188 offset:16384
	ds_read_b128 v[190:193], v188 offset:17408
	ds_read_b128 v[210:213], v188 offset:18432
	ds_read_b128 v[214:217], v188 offset:19456
	ds_read_b128 v[218:221], v188 offset:20480
	ds_read_b128 v[222:225], v188 offset:21504
	ds_read_b128 v[226:229], v188 offset:22528
	ds_read_b128 v[230:233], v188 offset:23552
	global_load_lds_dwordx4 v[234:235], off
	s_add_i32 m0, s5, 0x2000
	s_add_u32 s34, s48, 0x80000
	v_lshl_add_u64 v[236:237], s[48:49], 0, v[2:3]
	s_addc_u32 s35, s49, 0
	s_add_i32 s4, s4, s24
	global_load_lds_dwordx4 v[236:237], off
	v_lshl_add_u64 v[238:239], s[34:35], 0, v[4:5]
	s_mov_b32 m0, s4
	v_lshl_add_u64 v[240:241], s[52:53], 0, v[168:169]
	global_load_lds_dwordx4 v[238:239], off
	v_lshl_add_u64 v[238:239], s[34:35], 0, v[2:3]
	s_add_i32 m0, s4, 0x2000
	s_nop 0
	global_load_lds_dwordx4 v[238:239], off
	v_lshl_add_u64 v[238:239], s[52:53], 0, v[170:171]
	s_mov_b32 m0, s54
	s_nop 0
	global_load_lds_dwordx4 v[238:239], off
	s_mov_b32 m0, s55
	s_nop 0
	global_load_lds_dwordx4 v[240:241], off
	s_waitcnt vmcnt(8)
	s_waitcnt lgkmcnt(0)
	s_barrier
; #define PG8_STAGE(bufoff, gbase, voff) do { _Pragma("unroll") for (int _i = 0; _i < 2; ++_i) \
;         __builtin_amdgcn_global_load_lds((const unsigned*)((const char*)(gbase) + (voff)[_i]), (PG8_LAS unsigned*)(lds + (bufoff) + ldsw + _i * 8192), 16, 0, 0); } while (0)
; #define PG8_LDA(dst, b, h) do { _Pragma("unroll") for (int m = 0; m < 4; ++m) _Pragma("unroll") for (int k = 0; k < 2; ++k) dst[m][k] = *(const PG8_LAS bf16x8*)(lds + PG8_SA(b, h) + aoff + m * 2048 + k * 1024); } while (0)
; #define PG8_LDB(dst, b, h) do { _Pragma("unroll") for (int n = 0; n < 2; ++n) _Pragma("unroll") for (int k = 0; k < 2; ++k) dst[n][k] = *(const PG8_LAS bf16x8*)(lds + PG8_SB(b, h) + boff + n * 2048 + k * 1024); } while (0)
; #define PG8_MMA(ai, bj, At, Bt) do { __builtin_amdgcn_s_setprio(1); _Pragma("unroll") for (int m = 0; m < 4; ++m) _Pragma("unroll") for (int n = 0; n < 2; ++n) _Pragma("unroll") for (int k = 0; k < 2; ++k) \
;         acc[ai][bj][m][n] = __builtin_amdgcn_mfma_f32_16x16x32_bf16(Bt[n][k], At[m][k], acc[ai][bj][m][n], 0, 0, 0); __builtin_amdgcn_s_setprio(0); } while (0)
; #define PG8_WAIT_V(n) asm volatile("s_waitcnt vmcnt(" #n ")" ::: "memory")
; #define PG8_WAIT_L(n) asm volatile("s_waitcnt lgkmcnt(" #n ")" ::: "memory")
; #define PG8_BAR __builtin_amdgcn_s_barrier()
; #define PG8_SCHED __builtin_amdgcn_sched_barrier(0)
; template <class Epi, class Sched, bool ALIGN_EPI = false, bool SP2 = false>
; __device__ __forceinline__ void gemm_phase(PG8_LAS unsigned char* lds, const Gemm g, const Sched& S, const Epi& E) {
;     ...
;             PG8_WAIT_V(8); PG8_WAIT_L(0); PG8_BAR; PG8_MMA(1, 0, At, B0); PG8_MMA(1, 1, At, B1); PG8_BAR; PG8_SCHED;
;             PG8_LDB(B0, 1, 0); PG8_LDB(B1, 1, 1); PG8_SCHED; PG8_LDA(At, 1, 0); PG8_STAGE(PG8_SA(0, 1), a2 + hstep, voffA);
;             PG8_WAIT_V(8); PG8_WAIT_L(0); PG8_BAR; PG8_MMA(0, 0, At, B0); PG8_MMA(0, 1, At, B1); PG8_BAR; PG8_SCHED;
	v_mfma_f32_16x16x32_bf16 v[58:61], v[134:137], v[184:187], v[58:61]
	v_mfma_f32_16x16x32_bf16 v[58:61], v[138:141], v[190:193], v[58:61]
	v_mfma_f32_16x16x32_bf16 v[54:57], v[142:145], v[184:187], v[54:57]
	v_mfma_f32_16x16x32_bf16 v[54:57], v[146:149], v[190:193], v[54:57]
	v_mfma_f32_16x16x32_bf16 v[50:53], v[134:137], v[210:213], v[50:53]
	v_mfma_f32_16x16x32_bf16 v[50:53], v[138:141], v[214:217], v[50:53]
	v_mfma_f32_16x16x32_bf16 v[42:45], v[142:145], v[210:213], v[42:45]
	v_mfma_f32_16x16x32_bf16 v[42:45], v[146:149], v[214:217], v[42:45]
	v_mfma_f32_16x16x32_bf16 v[34:37], v[134:137], v[218:221], v[34:37]
	v_mfma_f32_16x16x32_bf16 v[34:37], v[138:141], v[222:225], v[34:37]
	v_mfma_f32_16x16x32_bf16 v[26:29], v[142:145], v[218:221], v[26:29]
	v_mfma_f32_16x16x32_bf16 v[26:29], v[146:149], v[222:225], v[26:29]
	v_mfma_f32_16x16x32_bf16 v[18:21], v[134:137], v[226:229], v[18:21]
	v_mfma_f32_16x16x32_bf16 v[18:21], v[138:141], v[230:233], v[18:21]
	v_mfma_f32_16x16x32_bf16 v[10:13], v[142:145], v[226:229], v[10:13]
	v_mfma_f32_16x16x32_bf16 v[10:13], v[146:149], v[230:233], v[10:13]
	v_mfma_f32_16x16x32_bf16 v[66:69], v[150:153], v[184:187], v[66:69]
	v_mfma_f32_16x16x32_bf16 v[66:69], v[154:157], v[190:193], v[66:69]
	v_mfma_f32_16x16x32_bf16 v[62:65], v[176:179], v[184:187], v[62:65]
	v_mfma_f32_16x16x32_bf16 v[62:65], v[180:183], v[190:193], v[62:65]
	v_mfma_f32_16x16x32_bf16 v[46:49], v[150:153], v[210:213], v[46:49]
	v_mfma_f32_16x16x32_bf16 v[46:49], v[154:157], v[214:217], v[46:49]
	v_mfma_f32_16x16x32_bf16 v[38:41], v[176:179], v[210:213], v[38:41]
	v_mfma_f32_16x16x32_bf16 v[38:41], v[180:183], v[214:217], v[38:41]
	v_mfma_f32_16x16x32_bf16 v[30:33], v[150:153], v[218:221], v[30:33]
	v_mfma_f32_16x16x32_bf16 v[30:33], v[154:157], v[222:225], v[30:33]
	v_mfma_f32_16x16x32_bf16 v[22:25], v[176:179], v[218:221], v[22:25]
	v_mfma_f32_16x16x32_bf16 v[22:25], v[180:183], v[222:225], v[22:25]
	v_mfma_f32_16x16x32_bf16 v[14:17], v[150:153], v[226:229], v[14:17]
	v_mfma_f32_16x16x32_bf16 v[14:17], v[154:157], v[230:233], v[14:17]
	v_mfma_f32_16x16x32_bf16 v[6:9], v[176:179], v[226:229], v[6:9]
	v_mfma_f32_16x16x32_bf16 v[6:9], v[180:183], v[230:233], v[6:9]
	s_barrier
	s_add_i32 s4, 0, 0x18000
	s_add_i32 s5, 0, 0x1c000
	v_add_u32_e32 v146, s4, v158
	v_add_u32_e32 v180, s5, v158
	ds_read_b128 v[134:137], v146
	ds_read_b128 v[138:141], v146 offset:1024
	ds_read_b128 v[142:145], v146 offset:2048
	ds_read_b128 v[146:149], v146 offset:3072
	ds_read_b128 v[150:153], v180
	ds_read_b128 v[154:157], v180 offset:1024
	ds_read_b128 v[176:179], v180 offset:2048
	ds_read_b128 v[180:183], v180 offset:3072
	s_add_u32 s34, s52, 0x80000
	s_addc_u32 s35, s53, 0
	s_mov_b32 m0, s56
	v_lshl_add_u64 v[242:243], s[34:35], 0, v[170:171]
	ds_read_b128 v[184:187], v188 offset:32768
	ds_read_b128 v[190:193], v188 offset:33792
	ds_read_b128 v[210:213], v188 offset:34816
	ds_read_b128 v[214:217], v188 offset:35840
	ds_read_b128 v[218:221], v188 offset:36864
	ds_read_b128 v[222:225], v188 offset:37888
	ds_read_b128 v[226:229], v188 offset:38912
	ds_read_b128 v[230:233], v188 offset:39936
	global_load_lds_dwordx4 v[242:243], off
	v_lshl_add_u64 v[242:243], s[34:35], 0, v[168:169]
	s_mov_b32 m0, s57
	s_nop 0
	global_load_lds_dwordx4 v[242:243], off
	s_waitcnt vmcnt(8)
	s_waitcnt lgkmcnt(0)
	s_barrier
	v_mfma_f32_16x16x32_bf16 v[122:125], v[134:137], v[184:187], v[122:125]
	v_mfma_f32_16x16x32_bf16 v[122:125], v[138:141], v[190:193], v[122:125]
	v_mfma_f32_16x16x32_bf16 v[118:121], v[142:145], v[184:187], v[118:121]
	v_mfma_f32_16x16x32_bf16 v[118:121], v[146:149], v[190:193], v[118:121]
	v_mfma_f32_16x16x32_bf16 v[114:117], v[134:137], v[210:213], v[114:117]
	v_mfma_f32_16x16x32_bf16 v[114:117], v[138:141], v[214:217], v[114:117]
	v_mfma_f32_16x16x32_bf16 v[106:109], v[142:145], v[210:213], v[106:109]
	v_mfma_f32_16x16x32_bf16 v[106:109], v[146:149], v[214:217], v[106:109]
	v_mfma_f32_16x16x32_bf16 v[98:101], v[134:137], v[218:221], v[98:101]
	v_mfma_f32_16x16x32_bf16 v[98:101], v[138:141], v[222:225], v[98:101]
	v_mfma_f32_16x16x32_bf16 v[90:93], v[142:145], v[218:221], v[90:93]
	v_mfma_f32_16x16x32_bf16 v[90:93], v[146:149], v[222:225], v[90:93]
	v_mfma_f32_16x16x32_bf16 v[82:85], v[134:137], v[226:229], v[82:85]
	v_mfma_f32_16x16x32_bf16 v[82:85], v[138:141], v[230:233], v[82:85]
	v_mfma_f32_16x16x32_bf16 v[74:77], v[142:145], v[226:229], v[74:77]
	v_mfma_f32_16x16x32_bf16 v[74:77], v[146:149], v[230:233], v[74:77]
	v_mfma_f32_16x16x32_bf16 v[130:133], v[150:153], v[184:187], v[130:133]
	v_mfma_f32_16x16x32_bf16 v[130:133], v[154:157], v[190:193], v[130:133]
	v_mfma_f32_16x16x32_bf16 v[126:129], v[176:179], v[184:187], v[126:129]
	v_mfma_f32_16x16x32_bf16 v[126:129], v[180:183], v[190:193], v[126:129]
	v_mfma_f32_16x16x32_bf16 v[110:113], v[150:153], v[210:213], v[110:113]
	v_mfma_f32_16x16x32_bf16 v[110:113], v[154:157], v[214:217], v[110:113]
	v_mfma_f32_16x16x32_bf16 v[102:105], v[176:179], v[210:213], v[102:105]
	v_mfma_f32_16x16x32_bf16 v[102:105], v[180:183], v[214:217], v[102:105]
	v_mfma_f32_16x16x32_bf16 v[94:97], v[150:153], v[218:221], v[94:97]
	v_mfma_f32_16x16x32_bf16 v[94:97], v[154:157], v[222:225], v[94:97]
	v_mfma_f32_16x16x32_bf16 v[86:89], v[176:179], v[218:221], v[86:89]
	v_mfma_f32_16x16x32_bf16 v[86:89], v[180:183], v[222:225], v[86:89]
	v_mfma_f32_16x16x32_bf16 v[78:81], v[150:153], v[226:229], v[78:81]
	v_mfma_f32_16x16x32_bf16 v[78:81], v[154:157], v[230:233], v[78:81]
	v_mfma_f32_16x16x32_bf16 v[70:73], v[176:179], v[226:229], v[70:73]
	v_mfma_f32_16x16x32_bf16 v[70:73], v[180:183], v[230:233], v[70:73]
	s_barrier
; #define PG8_STAGE(bufoff, gbase, voff) do { _Pragma("unroll") for (int _i = 0; _i < 2; ++_i) \
;         __builtin_amdgcn_global_load_lds((const unsigned*)((const char*)(gbase) + (voff)[_i]), (PG8_LAS unsigned*)(lds + (bufoff) + ldsw + _i * 8192), 16, 0, 0); } while (0)
; #define PG8_LDA(dst, b, h) do { _Pragma("unroll") for (int m = 0; m < 4; ++m) _Pragma("unroll") for (int k = 0; k < 2; ++k) dst[m][k] = *(const PG8_LAS bf16x8*)(lds + PG8_SA(b, h) + aoff + m * 2048 + k * 1024); } while (0)
; #define PG8_MMA(ai, bj, At, Bt) do { __builtin_amdgcn_s_setprio(1); _Pragma("unroll") for (int m = 0; m < 4; ++m) _Pragma("unroll") for (int n = 0; n < 2; ++n) _Pragma("unroll") for (int k = 0; k < 2; ++k) \
;         acc[ai][bj][m][n] = __builtin_amdgcn_mfma_f32_16x16x32_bf16(Bt[n][k], At[m][k], acc[ai][bj][m][n], 0, 0, 0); __builtin_amdgcn_s_setprio(0); } while (0)
; #define PG8_WAIT_V(n) asm volatile("s_waitcnt vmcnt(" #n ")" ::: "memory")
; #define PG8_WAIT_L(n) asm volatile("s_waitcnt lgkmcnt(" #n ")" ::: "memory")
; #define PG8_BAR __builtin_amdgcn_s_barrier()
; #define PG8_SCHED __builtin_amdgcn_sched_barrier(0)
; template <class Epi, class Sched, bool ALIGN_EPI = false, bool SP2 = false>
; __device__ __forceinline__ void gemm_phase(PG8_LAS unsigned char* lds, const Gemm g, const Sched& S, const Epi& E) {
;     ...
;         for (int t = 0; t < nt; t += 2) {
;     ...
;             PG8_LDA(At, 1, 1); PG8_STAGE(PG8_SB(1, 0), b3, voffB); PG8_STAGE(PG8_SB(1, 1), b3 + hstep, voffB); PG8_STAGE(PG8_SA(1, 0), a3, voffA);
;             PG8_WAIT_V(8); PG8_WAIT_L(0); PG8_BAR; PG8_MMA(1, 0, At, B0); PG8_MMA(1, 1, At, B1); PG8_BAR; PG8_SCHED;
	s_add_i32 s4, s4, s24
	v_lshl_add_u64 v[234:235], v[234:235], 0, s[28:29]
	s_mov_b32 m0, s4
	ds_read_b128 v[184:187], v188 offset:49152
	ds_read_b128 v[190:193], v188 offset:50176
	ds_read_b128 v[210:213], v188 offset:51200
	ds_read_b128 v[214:217], v188 offset:52224
	ds_read_b128 v[218:221], v188 offset:53248
	ds_read_b128 v[222:225], v188 offset:54272
	ds_read_b128 v[226:229], v188 offset:55296
	ds_read_b128 v[230:233], v188 offset:56320
	global_load_lds_dwordx4 v[234:235], off
	s_add_i32 m0, s4, 0x2000
	s_add_u32 s34, s48, 0x80080
	v_lshl_add_u64 v[234:235], v[236:237], 0, s[28:29]
	s_addc_u32 s35, s49, 0
	s_add_i32 s4, s5, s24
	global_load_lds_dwordx4 v[234:235], off
	v_lshl_add_u64 v[234:235], s[34:35], 0, v[4:5]
	s_mov_b32 m0, s4
	s_nop 0
	global_load_lds_dwordx4 v[234:235], off
	v_lshl_add_u64 v[234:235], s[34:35], 0, v[2:3]
	s_add_i32 m0, s4, 0x2000
	s_nop 0
	global_load_lds_dwordx4 v[234:235], off
	v_lshl_add_u64 v[234:235], v[238:239], 0, s[28:29]
	s_mov_b32 m0, s60
	s_nop 0
	global_load_lds_dwordx4 v[234:235], off
	v_lshl_add_u64 v[234:235], v[240:241], 0, s[28:29]
	s_mov_b32 m0, s61
	s_nop 0
	global_load_lds_dwordx4 v[234:235], off
	s_waitcnt vmcnt(8)
	s_waitcnt lgkmcnt(0)
	s_barrier
	v_mfma_f32_16x16x32_bf16 v[58:61], v[134:137], v[184:187], v[58:61]
	v_mfma_f32_16x16x32_bf16 v[58:61], v[138:141], v[190:193], v[58:61]
	v_mfma_f32_16x16x32_bf16 v[54:57], v[142:145], v[184:187], v[54:57]
	v_mfma_f32_16x16x32_bf16 v[54:57], v[146:149], v[190:193], v[54:57]
	v_mfma_f32_16x16x32_bf16 v[50:53], v[134:137], v[210:213], v[50:53]
	v_mfma_f32_16x16x32_bf16 v[50:53], v[138:141], v[214:217], v[50:53]
	v_mfma_f32_16x16x32_bf16 v[42:45], v[142:145], v[210:213], v[42:45]
	v_mfma_f32_16x16x32_bf16 v[42:45], v[146:149], v[214:217], v[42:45]
	v_mfma_f32_16x16x32_bf16 v[34:37], v[134:137], v[218:221], v[34:37]
	v_mfma_f32_16x16x32_bf16 v[34:37], v[138:141], v[222:225], v[34:37]
	v_mfma_f32_16x16x32_bf16 v[26:29], v[142:145], v[218:221], v[26:29]
	v_mfma_f32_16x16x32_bf16 v[26:29], v[146:149], v[222:225], v[26:29]
	v_mfma_f32_16x16x32_bf16 v[18:21], v[134:137], v[226:229], v[18:21]
	v_mfma_f32_16x16x32_bf16 v[18:21], v[138:141], v[230:233], v[18:21]
	v_mfma_f32_16x16x32_bf16 v[10:13], v[142:145], v[226:229], v[10:13]
	v_mfma_f32_16x16x32_bf16 v[10:13], v[146:149], v[230:233], v[10:13]
	v_mfma_f32_16x16x32_bf16 v[66:69], v[150:153], v[184:187], v[66:69]
	v_mfma_f32_16x16x32_bf16 v[66:69], v[154:157], v[190:193], v[66:69]
	v_mfma_f32_16x16x32_bf16 v[62:65], v[176:179], v[184:187], v[62:65]
	v_mfma_f32_16x16x32_bf16 v[62:65], v[180:183], v[190:193], v[62:65]
	v_mfma_f32_16x16x32_bf16 v[46:49], v[150:153], v[210:213], v[46:49]
	v_mfma_f32_16x16x32_bf16 v[46:49], v[154:157], v[214:217], v[46:49]
	v_mfma_f32_16x16x32_bf16 v[38:41], v[176:179], v[210:213], v[38:41]
	v_mfma_f32_16x16x32_bf16 v[38:41], v[180:183], v[214:217], v[38:41]
	v_mfma_f32_16x16x32_bf16 v[30:33], v[150:153], v[218:221], v[30:33]
	v_mfma_f32_16x16x32_bf16 v[30:33], v[154:157], v[222:225], v[30:33]
	v_mfma_f32_16x16x32_bf16 v[22:25], v[176:179], v[218:221], v[22:25]
	v_mfma_f32_16x16x32_bf16 v[22:25], v[180:183], v[222:225], v[22:25]
	v_mfma_f32_16x16x32_bf16 v[14:17], v[150:153], v[226:229], v[14:17]
	v_mfma_f32_16x16x32_bf16 v[14:17], v[154:157], v[230:233], v[14:17]
	v_mfma_f32_16x16x32_bf16 v[6:9], v[176:179], v[226:229], v[6:9]
	v_mfma_f32_16x16x32_bf16 v[6:9], v[180:183], v[230:233], v[6:9]
	s_barrier
	s_add_i32 s20, s20, 2
	s_add_u32 s50, s50, 0x100
	s_addc_u32 s51, s51, 0
	s_add_u32 s69, s69, 0x100
	s_addc_u32 s71, s71, 0
	s_cmp_gt_u32 s20, 29
	s_cbranch_scc0 .LBB0_1738
	s_and_b64 vcc, exec, s[40:41]
	s_cbranch_vccz .LBB0_1741
	s_barrier
